# fold_items inner loops rewritten: M slice staged via LDS broadcast, all outputs of an item in parallel
# speedup vs baseline: 1.0128x; 1.0128x over previous
.LBB0_165:
	s_cmp_eq_u32 s6, 1
	s_movk_i32 s7, 0x500
	s_cselect_b32 s7, s7, 0x900
	s_cmp_gt_u32 s25, 3
	s_cselect_b32 s9, s7, 0x400
	s_cmp_eq_u32 s6, 2
	s_cselect_b64 s[6:7], -1, 0
	s_or_b32 s9, s17, s9
	s_add_i32 s9, s9, s26
	s_add_i32 s8, s17, s8
	s_lshl_b32 s9, s9, 11
	s_add_u32 s9, s23, s9
	s_addc_u32 s25, s22, 0
	v_add_u32_e32 v68, s24, v70
	s_add_u32 s24, s15, s9
	v_ashrrev_i32_e32 v69, 31, v68
	s_addc_u32 s25, s16, s25
	v_lshl_add_u64 v[68:69], v[68:69], 1, s[24:25]
	s_add_u32 s24, s10, s18
	s_addc_u32 s25, s11, 0
	s_mov_b64 s[10:11], 0
	s_lshl_b32 s26, s68, 6
	v_lshlrev_b32_e32 v71, 4, v70
	v_lshrrev_b32_e32 v65, 2, v70
	v_and_b32_e32 v86, 3, v70
	v_lshlrev_b32_e32 v65, 8, v65
	v_lshl_add_u32 v65, v86, 4, v65
	v_add_u32_e32 v71, s26, v71
	global_load_dwordx4 v[88:91], v65, s[24:25]
	v_add_u32_e32 v86, 0x1000, v65
	v_add_u32_e32 v87, 0x2000, v65
	global_load_dwordx4 v[92:95], v86, s[24:25]
	v_add_u32_e32 v65, 0x3000, v65
	global_load_dwordx4 v[96:99], v87, s[24:25]
	s_nop 0
	global_load_dwordx4 v[100:103], v65, s[24:25]
	s_waitcnt vmcnt(0)
	ds_write_b128 v71, v[88:91]
	ds_write_b128 v71, v[92:95] offset:1024
	ds_write_b128 v71, v[96:99] offset:2048
	ds_write_b128 v71, v[100:103] offset:3072
	v_mov_b32_e32 v65, s26
	s_waitcnt lgkmcnt(0)
	ds_read_b128 v[88:91], v65 offset:0
	ds_read_b128 v[92:95], v65 offset:16
	ds_read_b128 v[96:99], v65 offset:32
	ds_read_b128 v[100:103], v65 offset:48
	ds_read_b128 v[104:107], v65 offset:64
	ds_read_b128 v[108:111], v65 offset:80
	ds_read_b128 v[112:115], v65 offset:96
	ds_read_b128 v[116:119], v65 offset:112
	ds_read_b128 v[120:123], v65 offset:128
	ds_read_b128 v[124:127], v65 offset:144
	ds_read_b128 v[128:131], v65 offset:160
	ds_read_b128 v[132:135], v65 offset:176
	s_waitcnt lgkmcnt(8)
	v_pk_mul_f32 v[72:73], v[12:13], v[88:89] op_sel_hi:[0,1]
	v_pk_mul_f32 v[74:75], v[12:13], v[90:91] op_sel_hi:[0,1]
	v_pk_mul_f32 v[76:77], v[12:13], v[92:93] op_sel_hi:[0,1]
	v_pk_mul_f32 v[78:79], v[12:13], v[94:95] op_sel_hi:[0,1]
	v_pk_mul_f32 v[80:81], v[12:13], v[96:97] op_sel_hi:[0,1]
	v_pk_mul_f32 v[82:83], v[12:13], v[98:99] op_sel_hi:[0,1]
	v_pk_mul_f32 v[84:85], v[12:13], v[100:101] op_sel_hi:[0,1]
	v_pk_mul_f32 v[86:87], v[12:13], v[102:103] op_sel_hi:[0,1]
	ds_read_b128 v[88:91], v65 offset:192
	ds_read_b128 v[92:95], v65 offset:208
	ds_read_b128 v[96:99], v65 offset:224
	ds_read_b128 v[100:103], v65 offset:240
	s_waitcnt lgkmcnt(8)
	v_pk_fma_f32 v[72:73], v[12:13], v[104:105], v[72:73] op_sel:[1,0,0] op_sel_hi:[1,1,1]
	v_pk_fma_f32 v[74:75], v[12:13], v[106:107], v[74:75] op_sel:[1,0,0] op_sel_hi:[1,1,1]
	v_pk_fma_f32 v[76:77], v[12:13], v[108:109], v[76:77] op_sel:[1,0,0] op_sel_hi:[1,1,1]
	v_pk_fma_f32 v[78:79], v[12:13], v[110:111], v[78:79] op_sel:[1,0,0] op_sel_hi:[1,1,1]
	v_pk_fma_f32 v[80:81], v[12:13], v[112:113], v[80:81] op_sel:[1,0,0] op_sel_hi:[1,1,1]
	v_pk_fma_f32 v[82:83], v[12:13], v[114:115], v[82:83] op_sel:[1,0,0] op_sel_hi:[1,1,1]
	v_pk_fma_f32 v[84:85], v[12:13], v[116:117], v[84:85] op_sel:[1,0,0] op_sel_hi:[1,1,1]
	v_pk_fma_f32 v[86:87], v[12:13], v[118:119], v[86:87] op_sel:[1,0,0] op_sel_hi:[1,1,1]
	ds_read_b128 v[104:107], v65 offset:256
	ds_read_b128 v[108:111], v65 offset:272
	ds_read_b128 v[112:115], v65 offset:288
	ds_read_b128 v[116:119], v65 offset:304
	s_waitcnt lgkmcnt(8)
	v_pk_fma_f32 v[72:73], v[14:15], v[120:121], v[72:73] op_sel_hi:[0,1,1]
	v_pk_fma_f32 v[74:75], v[14:15], v[122:123], v[74:75] op_sel_hi:[0,1,1]
	v_pk_fma_f32 v[76:77], v[14:15], v[124:125], v[76:77] op_sel_hi:[0,1,1]
	v_pk_fma_f32 v[78:79], v[14:15], v[126:127], v[78:79] op_sel_hi:[0,1,1]
	v_pk_fma_f32 v[80:81], v[14:15], v[128:129], v[80:81] op_sel_hi:[0,1,1]
	v_pk_fma_f32 v[82:83], v[14:15], v[130:131], v[82:83] op_sel_hi:[0,1,1]
	v_pk_fma_f32 v[84:85], v[14:15], v[132:133], v[84:85] op_sel_hi:[0,1,1]
	v_pk_fma_f32 v[86:87], v[14:15], v[134:135], v[86:87] op_sel_hi:[0,1,1]
	ds_read_b128 v[120:123], v65 offset:320
	ds_read_b128 v[124:127], v65 offset:336
	ds_read_b128 v[128:131], v65 offset:352
	ds_read_b128 v[132:135], v65 offset:368
	s_waitcnt lgkmcnt(8)
	v_pk_fma_f32 v[72:73], v[14:15], v[88:89], v[72:73] op_sel:[1,0,0] op_sel_hi:[1,1,1]
	v_pk_fma_f32 v[74:75], v[14:15], v[90:91], v[74:75] op_sel:[1,0,0] op_sel_hi:[1,1,1]
	v_pk_fma_f32 v[76:77], v[14:15], v[92:93], v[76:77] op_sel:[1,0,0] op_sel_hi:[1,1,1]
	v_pk_fma_f32 v[78:79], v[14:15], v[94:95], v[78:79] op_sel:[1,0,0] op_sel_hi:[1,1,1]
	v_pk_fma_f32 v[80:81], v[14:15], v[96:97], v[80:81] op_sel:[1,0,0] op_sel_hi:[1,1,1]
	v_pk_fma_f32 v[82:83], v[14:15], v[98:99], v[82:83] op_sel:[1,0,0] op_sel_hi:[1,1,1]
	v_pk_fma_f32 v[84:85], v[14:15], v[100:101], v[84:85] op_sel:[1,0,0] op_sel_hi:[1,1,1]
	v_pk_fma_f32 v[86:87], v[14:15], v[102:103], v[86:87] op_sel:[1,0,0] op_sel_hi:[1,1,1]
	ds_read_b128 v[88:91], v65 offset:384
	ds_read_b128 v[92:95], v65 offset:400
	ds_read_b128 v[96:99], v65 offset:416
	ds_read_b128 v[100:103], v65 offset:432
	s_waitcnt lgkmcnt(8)
	v_pk_fma_f32 v[72:73], v[8:9], v[104:105], v[72:73] op_sel_hi:[0,1,1]
	v_pk_fma_f32 v[74:75], v[8:9], v[106:107], v[74:75] op_sel_hi:[0,1,1]
	v_pk_fma_f32 v[76:77], v[8:9], v[108:109], v[76:77] op_sel_hi:[0,1,1]
	v_pk_fma_f32 v[78:79], v[8:9], v[110:111], v[78:79] op_sel_hi:[0,1,1]
	v_pk_fma_f32 v[80:81], v[8:9], v[112:113], v[80:81] op_sel_hi:[0,1,1]
	v_pk_fma_f32 v[82:83], v[8:9], v[114:115], v[82:83] op_sel_hi:[0,1,1]
	v_pk_fma_f32 v[84:85], v[8:9], v[116:117], v[84:85] op_sel_hi:[0,1,1]
	v_pk_fma_f32 v[86:87], v[8:9], v[118:119], v[86:87] op_sel_hi:[0,1,1]
	ds_read_b128 v[104:107], v65 offset:448
	ds_read_b128 v[108:111], v65 offset:464
	ds_read_b128 v[112:115], v65 offset:480
	ds_read_b128 v[116:119], v65 offset:496
	s_waitcnt lgkmcnt(8)
	v_pk_fma_f32 v[72:73], v[8:9], v[120:121], v[72:73] op_sel:[1,0,0] op_sel_hi:[1,1,1]
	v_pk_fma_f32 v[74:75], v[8:9], v[122:123], v[74:75] op_sel:[1,0,0] op_sel_hi:[1,1,1]
	v_pk_fma_f32 v[76:77], v[8:9], v[124:125], v[76:77] op_sel:[1,0,0] op_sel_hi:[1,1,1]
	v_pk_fma_f32 v[78:79], v[8:9], v[126:127], v[78:79] op_sel:[1,0,0] op_sel_hi:[1,1,1]
	v_pk_fma_f32 v[80:81], v[8:9], v[128:129], v[80:81] op_sel:[1,0,0] op_sel_hi:[1,1,1]
	v_pk_fma_f32 v[82:83], v[8:9], v[130:131], v[82:83] op_sel:[1,0,0] op_sel_hi:[1,1,1]
	v_pk_fma_f32 v[84:85], v[8:9], v[132:133], v[84:85] op_sel:[1,0,0] op_sel_hi:[1,1,1]
	v_pk_fma_f32 v[86:87], v[8:9], v[134:135], v[86:87] op_sel:[1,0,0] op_sel_hi:[1,1,1]
	ds_read_b128 v[120:123], v65 offset:512
	ds_read_b128 v[124:127], v65 offset:528
	ds_read_b128 v[128:131], v65 offset:544
	ds_read_b128 v[132:135], v65 offset:560
	s_waitcnt lgkmcnt(8)
	v_pk_fma_f32 v[72:73], v[10:11], v[88:89], v[72:73] op_sel_hi:[0,1,1]
	v_pk_fma_f32 v[74:75], v[10:11], v[90:91], v[74:75] op_sel_hi:[0,1,1]
	v_pk_fma_f32 v[76:77], v[10:11], v[92:93], v[76:77] op_sel_hi:[0,1,1]
	v_pk_fma_f32 v[78:79], v[10:11], v[94:95], v[78:79] op_sel_hi:[0,1,1]
	v_pk_fma_f32 v[80:81], v[10:11], v[96:97], v[80:81] op_sel_hi:[0,1,1]
	v_pk_fma_f32 v[82:83], v[10:11], v[98:99], v[82:83] op_sel_hi:[0,1,1]
	v_pk_fma_f32 v[84:85], v[10:11], v[100:101], v[84:85] op_sel_hi:[0,1,1]
	v_pk_fma_f32 v[86:87], v[10:11], v[102:103], v[86:87] op_sel_hi:[0,1,1]
	ds_read_b128 v[88:91], v65 offset:576
	ds_read_b128 v[92:95], v65 offset:592
	ds_read_b128 v[96:99], v65 offset:608
	ds_read_b128 v[100:103], v65 offset:624
	s_waitcnt lgkmcnt(8)
	v_pk_fma_f32 v[72:73], v[10:11], v[104:105], v[72:73] op_sel:[1,0,0] op_sel_hi:[1,1,1]
	v_pk_fma_f32 v[74:75], v[10:11], v[106:107], v[74:75] op_sel:[1,0,0] op_sel_hi:[1,1,1]
	v_pk_fma_f32 v[76:77], v[10:11], v[108:109], v[76:77] op_sel:[1,0,0] op_sel_hi:[1,1,1]
	v_pk_fma_f32 v[78:79], v[10:11], v[110:111], v[78:79] op_sel:[1,0,0] op_sel_hi:[1,1,1]
	v_pk_fma_f32 v[80:81], v[10:11], v[112:113], v[80:81] op_sel:[1,0,0] op_sel_hi:[1,1,1]
	v_pk_fma_f32 v[82:83], v[10:11], v[114:115], v[82:83] op_sel:[1,0,0] op_sel_hi:[1,1,1]
	v_pk_fma_f32 v[84:85], v[10:11], v[116:117], v[84:85] op_sel:[1,0,0] op_sel_hi:[1,1,1]
	v_pk_fma_f32 v[86:87], v[10:11], v[118:119], v[86:87] op_sel:[1,0,0] op_sel_hi:[1,1,1]
	ds_read_b128 v[104:107], v65 offset:640
	ds_read_b128 v[108:111], v65 offset:656
	ds_read_b128 v[112:115], v65 offset:672
	ds_read_b128 v[116:119], v65 offset:688
	s_waitcnt lgkmcnt(8)
	v_pk_fma_f32 v[72:73], v[4:5], v[120:121], v[72:73] op_sel_hi:[0,1,1]
	v_pk_fma_f32 v[74:75], v[4:5], v[122:123], v[74:75] op_sel_hi:[0,1,1]
	v_pk_fma_f32 v[76:77], v[4:5], v[124:125], v[76:77] op_sel_hi:[0,1,1]
	v_pk_fma_f32 v[78:79], v[4:5], v[126:127], v[78:79] op_sel_hi:[0,1,1]
	v_pk_fma_f32 v[80:81], v[4:5], v[128:129], v[80:81] op_sel_hi:[0,1,1]
	v_pk_fma_f32 v[82:83], v[4:5], v[130:131], v[82:83] op_sel_hi:[0,1,1]
	v_pk_fma_f32 v[84:85], v[4:5], v[132:133], v[84:85] op_sel_hi:[0,1,1]
	v_pk_fma_f32 v[86:87], v[4:5], v[134:135], v[86:87] op_sel_hi:[0,1,1]
	ds_read_b128 v[120:123], v65 offset:704
	ds_read_b128 v[124:127], v65 offset:720
	ds_read_b128 v[128:131], v65 offset:736
	ds_read_b128 v[132:135], v65 offset:752
	s_waitcnt lgkmcnt(8)
	v_pk_fma_f32 v[72:73], v[4:5], v[88:89], v[72:73] op_sel:[1,0,0] op_sel_hi:[1,1,1]
	v_pk_fma_f32 v[74:75], v[4:5], v[90:91], v[74:75] op_sel:[1,0,0] op_sel_hi:[1,1,1]
	v_pk_fma_f32 v[76:77], v[4:5], v[92:93], v[76:77] op_sel:[1,0,0] op_sel_hi:[1,1,1]
	v_pk_fma_f32 v[78:79], v[4:5], v[94:95], v[78:79] op_sel:[1,0,0] op_sel_hi:[1,1,1]
	v_pk_fma_f32 v[80:81], v[4:5], v[96:97], v[80:81] op_sel:[1,0,0] op_sel_hi:[1,1,1]
	v_pk_fma_f32 v[82:83], v[4:5], v[98:99], v[82:83] op_sel:[1,0,0] op_sel_hi:[1,1,1]
	v_pk_fma_f32 v[84:85], v[4:5], v[100:101], v[84:85] op_sel:[1,0,0] op_sel_hi:[1,1,1]
	v_pk_fma_f32 v[86:87], v[4:5], v[102:103], v[86:87] op_sel:[1,0,0] op_sel_hi:[1,1,1]
	ds_read_b128 v[88:91], v65 offset:768
	ds_read_b128 v[92:95], v65 offset:784
	ds_read_b128 v[96:99], v65 offset:800
	ds_read_b128 v[100:103], v65 offset:816
	s_waitcnt lgkmcnt(8)
	v_pk_fma_f32 v[72:73], v[6:7], v[104:105], v[72:73] op_sel_hi:[0,1,1]
	v_pk_fma_f32 v[74:75], v[6:7], v[106:107], v[74:75] op_sel_hi:[0,1,1]
	v_pk_fma_f32 v[76:77], v[6:7], v[108:109], v[76:77] op_sel_hi:[0,1,1]
	v_pk_fma_f32 v[78:79], v[6:7], v[110:111], v[78:79] op_sel_hi:[0,1,1]
	v_pk_fma_f32 v[80:81], v[6:7], v[112:113], v[80:81] op_sel_hi:[0,1,1]
	v_pk_fma_f32 v[82:83], v[6:7], v[114:115], v[82:83] op_sel_hi:[0,1,1]
	v_pk_fma_f32 v[84:85], v[6:7], v[116:117], v[84:85] op_sel_hi:[0,1,1]
	v_pk_fma_f32 v[86:87], v[6:7], v[118:119], v[86:87] op_sel_hi:[0,1,1]
	ds_read_b128 v[104:107], v65 offset:832
	ds_read_b128 v[108:111], v65 offset:848
	ds_read_b128 v[112:115], v65 offset:864
	ds_read_b128 v[116:119], v65 offset:880
	s_waitcnt lgkmcnt(8)
	v_pk_fma_f32 v[72:73], v[6:7], v[120:121], v[72:73] op_sel:[1,0,0] op_sel_hi:[1,1,1]
	v_pk_fma_f32 v[74:75], v[6:7], v[122:123], v[74:75] op_sel:[1,0,0] op_sel_hi:[1,1,1]
	v_pk_fma_f32 v[76:77], v[6:7], v[124:125], v[76:77] op_sel:[1,0,0] op_sel_hi:[1,1,1]
	v_pk_fma_f32 v[78:79], v[6:7], v[126:127], v[78:79] op_sel:[1,0,0] op_sel_hi:[1,1,1]
	v_pk_fma_f32 v[80:81], v[6:7], v[128:129], v[80:81] op_sel:[1,0,0] op_sel_hi:[1,1,1]
	v_pk_fma_f32 v[82:83], v[6:7], v[130:131], v[82:83] op_sel:[1,0,0] op_sel_hi:[1,1,1]
	v_pk_fma_f32 v[84:85], v[6:7], v[132:133], v[84:85] op_sel:[1,0,0] op_sel_hi:[1,1,1]
	v_pk_fma_f32 v[86:87], v[6:7], v[134:135], v[86:87] op_sel:[1,0,0] op_sel_hi:[1,1,1]
	ds_read_b128 v[120:123], v65 offset:896
	ds_read_b128 v[124:127], v65 offset:912
	ds_read_b128 v[128:131], v65 offset:928
	ds_read_b128 v[132:135], v65 offset:944
	s_waitcnt lgkmcnt(8)
	v_pk_fma_f32 v[72:73], v[0:1], v[88:89], v[72:73] op_sel_hi:[0,1,1]
	v_pk_fma_f32 v[74:75], v[0:1], v[90:91], v[74:75] op_sel_hi:[0,1,1]
	v_pk_fma_f32 v[76:77], v[0:1], v[92:93], v[76:77] op_sel_hi:[0,1,1]
	v_pk_fma_f32 v[78:79], v[0:1], v[94:95], v[78:79] op_sel_hi:[0,1,1]
	v_pk_fma_f32 v[80:81], v[0:1], v[96:97], v[80:81] op_sel_hi:[0,1,1]
	v_pk_fma_f32 v[82:83], v[0:1], v[98:99], v[82:83] op_sel_hi:[0,1,1]
	v_pk_fma_f32 v[84:85], v[0:1], v[100:101], v[84:85] op_sel_hi:[0,1,1]
	v_pk_fma_f32 v[86:87], v[0:1], v[102:103], v[86:87] op_sel_hi:[0,1,1]
	ds_read_b128 v[88:91], v65 offset:960
	ds_read_b128 v[92:95], v65 offset:976
	ds_read_b128 v[96:99], v65 offset:992
	ds_read_b128 v[100:103], v65 offset:1008
	s_waitcnt lgkmcnt(8)
	v_pk_fma_f32 v[72:73], v[0:1], v[104:105], v[72:73] op_sel:[1,0,0] op_sel_hi:[1,1,1]
	v_pk_fma_f32 v[74:75], v[0:1], v[106:107], v[74:75] op_sel:[1,0,0] op_sel_hi:[1,1,1]
	v_pk_fma_f32 v[76:77], v[0:1], v[108:109], v[76:77] op_sel:[1,0,0] op_sel_hi:[1,1,1]
	v_pk_fma_f32 v[78:79], v[0:1], v[110:111], v[78:79] op_sel:[1,0,0] op_sel_hi:[1,1,1]
	v_pk_fma_f32 v[80:81], v[0:1], v[112:113], v[80:81] op_sel:[1,0,0] op_sel_hi:[1,1,1]
	v_pk_fma_f32 v[82:83], v[0:1], v[114:115], v[82:83] op_sel:[1,0,0] op_sel_hi:[1,1,1]
	v_pk_fma_f32 v[84:85], v[0:1], v[116:117], v[84:85] op_sel:[1,0,0] op_sel_hi:[1,1,1]
	v_pk_fma_f32 v[86:87], v[0:1], v[118:119], v[86:87] op_sel:[1,0,0] op_sel_hi:[1,1,1]
	ds_read_b128 v[104:107], v65 offset:1024
	ds_read_b128 v[108:111], v65 offset:1040
	ds_read_b128 v[112:115], v65 offset:1056
	ds_read_b128 v[116:119], v65 offset:1072
	s_waitcnt lgkmcnt(8)
	v_pk_fma_f32 v[72:73], v[2:3], v[120:121], v[72:73] op_sel_hi:[0,1,1]
	v_pk_fma_f32 v[74:75], v[2:3], v[122:123], v[74:75] op_sel_hi:[0,1,1]
	v_pk_fma_f32 v[76:77], v[2:3], v[124:125], v[76:77] op_sel_hi:[0,1,1]
	v_pk_fma_f32 v[78:79], v[2:3], v[126:127], v[78:79] op_sel_hi:[0,1,1]
	v_pk_fma_f32 v[80:81], v[2:3], v[128:129], v[80:81] op_sel_hi:[0,1,1]
	v_pk_fma_f32 v[82:83], v[2:3], v[130:131], v[82:83] op_sel_hi:[0,1,1]
	v_pk_fma_f32 v[84:85], v[2:3], v[132:133], v[84:85] op_sel_hi:[0,1,1]
	v_pk_fma_f32 v[86:87], v[2:3], v[134:135], v[86:87] op_sel_hi:[0,1,1]
	ds_read_b128 v[120:123], v65 offset:1088
	ds_read_b128 v[124:127], v65 offset:1104
	ds_read_b128 v[128:131], v65 offset:1120
	ds_read_b128 v[132:135], v65 offset:1136
	s_waitcnt lgkmcnt(8)
	v_pk_fma_f32 v[72:73], v[2:3], v[88:89], v[72:73] op_sel:[1,0,0] op_sel_hi:[1,1,1]
	v_pk_fma_f32 v[74:75], v[2:3], v[90:91], v[74:75] op_sel:[1,0,0] op_sel_hi:[1,1,1]
	v_pk_fma_f32 v[76:77], v[2:3], v[92:93], v[76:77] op_sel:[1,0,0] op_sel_hi:[1,1,1]
	v_pk_fma_f32 v[78:79], v[2:3], v[94:95], v[78:79] op_sel:[1,0,0] op_sel_hi:[1,1,1]
	v_pk_fma_f32 v[80:81], v[2:3], v[96:97], v[80:81] op_sel:[1,0,0] op_sel_hi:[1,1,1]
	v_pk_fma_f32 v[82:83], v[2:3], v[98:99], v[82:83] op_sel:[1,0,0] op_sel_hi:[1,1,1]
	v_pk_fma_f32 v[84:85], v[2:3], v[100:101], v[84:85] op_sel:[1,0,0] op_sel_hi:[1,1,1]
	v_pk_fma_f32 v[86:87], v[2:3], v[102:103], v[86:87] op_sel:[1,0,0] op_sel_hi:[1,1,1]
	ds_read_b128 v[88:91], v65 offset:1152
	ds_read_b128 v[92:95], v65 offset:1168
	ds_read_b128 v[96:99], v65 offset:1184
	ds_read_b128 v[100:103], v65 offset:1200
	s_waitcnt lgkmcnt(8)
	v_pk_fma_f32 v[72:73], v[28:29], v[104:105], v[72:73] op_sel_hi:[0,1,1]
	v_pk_fma_f32 v[74:75], v[28:29], v[106:107], v[74:75] op_sel_hi:[0,1,1]
	v_pk_fma_f32 v[76:77], v[28:29], v[108:109], v[76:77] op_sel_hi:[0,1,1]
	v_pk_fma_f32 v[78:79], v[28:29], v[110:111], v[78:79] op_sel_hi:[0,1,1]
	v_pk_fma_f32 v[80:81], v[28:29], v[112:113], v[80:81] op_sel_hi:[0,1,1]
	v_pk_fma_f32 v[82:83], v[28:29], v[114:115], v[82:83] op_sel_hi:[0,1,1]
	v_pk_fma_f32 v[84:85], v[28:29], v[116:117], v[84:85] op_sel_hi:[0,1,1]
	v_pk_fma_f32 v[86:87], v[28:29], v[118:119], v[86:87] op_sel_hi:[0,1,1]
	ds_read_b128 v[104:107], v65 offset:1216
	ds_read_b128 v[108:111], v65 offset:1232
	ds_read_b128 v[112:115], v65 offset:1248
	ds_read_b128 v[116:119], v65 offset:1264
	s_waitcnt lgkmcnt(8)
	v_pk_fma_f32 v[72:73], v[28:29], v[120:121], v[72:73] op_sel:[1,0,0] op_sel_hi:[1,1,1]
	v_pk_fma_f32 v[74:75], v[28:29], v[122:123], v[74:75] op_sel:[1,0,0] op_sel_hi:[1,1,1]
	v_pk_fma_f32 v[76:77], v[28:29], v[124:125], v[76:77] op_sel:[1,0,0] op_sel_hi:[1,1,1]
	v_pk_fma_f32 v[78:79], v[28:29], v[126:127], v[78:79] op_sel:[1,0,0] op_sel_hi:[1,1,1]
	v_pk_fma_f32 v[80:81], v[28:29], v[128:129], v[80:81] op_sel:[1,0,0] op_sel_hi:[1,1,1]
	v_pk_fma_f32 v[82:83], v[28:29], v[130:131], v[82:83] op_sel:[1,0,0] op_sel_hi:[1,1,1]
	v_pk_fma_f32 v[84:85], v[28:29], v[132:133], v[84:85] op_sel:[1,0,0] op_sel_hi:[1,1,1]
	v_pk_fma_f32 v[86:87], v[28:29], v[134:135], v[86:87] op_sel:[1,0,0] op_sel_hi:[1,1,1]
	ds_read_b128 v[120:123], v65 offset:1280
	ds_read_b128 v[124:127], v65 offset:1296
	ds_read_b128 v[128:131], v65 offset:1312
	ds_read_b128 v[132:135], v65 offset:1328
	s_waitcnt lgkmcnt(8)
	v_pk_fma_f32 v[72:73], v[30:31], v[88:89], v[72:73] op_sel_hi:[0,1,1]
	v_pk_fma_f32 v[74:75], v[30:31], v[90:91], v[74:75] op_sel_hi:[0,1,1]
	v_pk_fma_f32 v[76:77], v[30:31], v[92:93], v[76:77] op_sel_hi:[0,1,1]
	v_pk_fma_f32 v[78:79], v[30:31], v[94:95], v[78:79] op_sel_hi:[0,1,1]
	v_pk_fma_f32 v[80:81], v[30:31], v[96:97], v[80:81] op_sel_hi:[0,1,1]
	v_pk_fma_f32 v[82:83], v[30:31], v[98:99], v[82:83] op_sel_hi:[0,1,1]
	v_pk_fma_f32 v[84:85], v[30:31], v[100:101], v[84:85] op_sel_hi:[0,1,1]
	v_pk_fma_f32 v[86:87], v[30:31], v[102:103], v[86:87] op_sel_hi:[0,1,1]
	ds_read_b128 v[88:91], v65 offset:1344
	ds_read_b128 v[92:95], v65 offset:1360
	ds_read_b128 v[96:99], v65 offset:1376
	ds_read_b128 v[100:103], v65 offset:1392
	s_waitcnt lgkmcnt(8)
	v_pk_fma_f32 v[72:73], v[30:31], v[104:105], v[72:73] op_sel:[1,0,0] op_sel_hi:[1,1,1]
	v_pk_fma_f32 v[74:75], v[30:31], v[106:107], v[74:75] op_sel:[1,0,0] op_sel_hi:[1,1,1]
	v_pk_fma_f32 v[76:77], v[30:31], v[108:109], v[76:77] op_sel:[1,0,0] op_sel_hi:[1,1,1]
	v_pk_fma_f32 v[78:79], v[30:31], v[110:111], v[78:79] op_sel:[1,0,0] op_sel_hi:[1,1,1]
	v_pk_fma_f32 v[80:81], v[30:31], v[112:113], v[80:81] op_sel:[1,0,0] op_sel_hi:[1,1,1]
	v_pk_fma_f32 v[82:83], v[30:31], v[114:115], v[82:83] op_sel:[1,0,0] op_sel_hi:[1,1,1]
	v_pk_fma_f32 v[84:85], v[30:31], v[116:117], v[84:85] op_sel:[1,0,0] op_sel_hi:[1,1,1]
	v_pk_fma_f32 v[86:87], v[30:31], v[118:119], v[86:87] op_sel:[1,0,0] op_sel_hi:[1,1,1]
	ds_read_b128 v[104:107], v65 offset:1408
	ds_read_b128 v[108:111], v65 offset:1424
	ds_read_b128 v[112:115], v65 offset:1440
	ds_read_b128 v[116:119], v65 offset:1456
	s_waitcnt lgkmcnt(8)
	v_pk_fma_f32 v[72:73], v[24:25], v[120:121], v[72:73] op_sel_hi:[0,1,1]
	v_pk_fma_f32 v[74:75], v[24:25], v[122:123], v[74:75] op_sel_hi:[0,1,1]
	v_pk_fma_f32 v[76:77], v[24:25], v[124:125], v[76:77] op_sel_hi:[0,1,1]
	v_pk_fma_f32 v[78:79], v[24:25], v[126:127], v[78:79] op_sel_hi:[0,1,1]
	v_pk_fma_f32 v[80:81], v[24:25], v[128:129], v[80:81] op_sel_hi:[0,1,1]
	v_pk_fma_f32 v[82:83], v[24:25], v[130:131], v[82:83] op_sel_hi:[0,1,1]
	v_pk_fma_f32 v[84:85], v[24:25], v[132:133], v[84:85] op_sel_hi:[0,1,1]
	v_pk_fma_f32 v[86:87], v[24:25], v[134:135], v[86:87] op_sel_hi:[0,1,1]
	ds_read_b128 v[120:123], v65 offset:1472
	ds_read_b128 v[124:127], v65 offset:1488
	ds_read_b128 v[128:131], v65 offset:1504
	ds_read_b128 v[132:135], v65 offset:1520
	s_waitcnt lgkmcnt(8)
	v_pk_fma_f32 v[72:73], v[24:25], v[88:89], v[72:73] op_sel:[1,0,0] op_sel_hi:[1,1,1]
	v_pk_fma_f32 v[74:75], v[24:25], v[90:91], v[74:75] op_sel:[1,0,0] op_sel_hi:[1,1,1]
	v_pk_fma_f32 v[76:77], v[24:25], v[92:93], v[76:77] op_sel:[1,0,0] op_sel_hi:[1,1,1]
	v_pk_fma_f32 v[78:79], v[24:25], v[94:95], v[78:79] op_sel:[1,0,0] op_sel_hi:[1,1,1]
	v_pk_fma_f32 v[80:81], v[24:25], v[96:97], v[80:81] op_sel:[1,0,0] op_sel_hi:[1,1,1]
	v_pk_fma_f32 v[82:83], v[24:25], v[98:99], v[82:83] op_sel:[1,0,0] op_sel_hi:[1,1,1]
	v_pk_fma_f32 v[84:85], v[24:25], v[100:101], v[84:85] op_sel:[1,0,0] op_sel_hi:[1,1,1]
	v_pk_fma_f32 v[86:87], v[24:25], v[102:103], v[86:87] op_sel:[1,0,0] op_sel_hi:[1,1,1]
	ds_read_b128 v[88:91], v65 offset:1536
	ds_read_b128 v[92:95], v65 offset:1552
	ds_read_b128 v[96:99], v65 offset:1568
	ds_read_b128 v[100:103], v65 offset:1584
	s_waitcnt lgkmcnt(8)
	v_pk_fma_f32 v[72:73], v[26:27], v[104:105], v[72:73] op_sel_hi:[0,1,1]
	v_pk_fma_f32 v[74:75], v[26:27], v[106:107], v[74:75] op_sel_hi:[0,1,1]
	v_pk_fma_f32 v[76:77], v[26:27], v[108:109], v[76:77] op_sel_hi:[0,1,1]
	v_pk_fma_f32 v[78:79], v[26:27], v[110:111], v[78:79] op_sel_hi:[0,1,1]
	v_pk_fma_f32 v[80:81], v[26:27], v[112:113], v[80:81] op_sel_hi:[0,1,1]
	v_pk_fma_f32 v[82:83], v[26:27], v[114:115], v[82:83] op_sel_hi:[0,1,1]
	v_pk_fma_f32 v[84:85], v[26:27], v[116:117], v[84:85] op_sel_hi:[0,1,1]
	v_pk_fma_f32 v[86:87], v[26:27], v[118:119], v[86:87] op_sel_hi:[0,1,1]
	ds_read_b128 v[104:107], v65 offset:1600
	ds_read_b128 v[108:111], v65 offset:1616
	ds_read_b128 v[112:115], v65 offset:1632
	ds_read_b128 v[116:119], v65 offset:1648
	s_waitcnt lgkmcnt(8)
	v_pk_fma_f32 v[72:73], v[26:27], v[120:121], v[72:73] op_sel:[1,0,0] op_sel_hi:[1,1,1]
	v_pk_fma_f32 v[74:75], v[26:27], v[122:123], v[74:75] op_sel:[1,0,0] op_sel_hi:[1,1,1]
	v_pk_fma_f32 v[76:77], v[26:27], v[124:125], v[76:77] op_sel:[1,0,0] op_sel_hi:[1,1,1]
	v_pk_fma_f32 v[78:79], v[26:27], v[126:127], v[78:79] op_sel:[1,0,0] op_sel_hi:[1,1,1]
	v_pk_fma_f32 v[80:81], v[26:27], v[128:129], v[80:81] op_sel:[1,0,0] op_sel_hi:[1,1,1]
	v_pk_fma_f32 v[82:83], v[26:27], v[130:131], v[82:83] op_sel:[1,0,0] op_sel_hi:[1,1,1]
	v_pk_fma_f32 v[84:85], v[26:27], v[132:133], v[84:85] op_sel:[1,0,0] op_sel_hi:[1,1,1]
	v_pk_fma_f32 v[86:87], v[26:27], v[134:135], v[86:87] op_sel:[1,0,0] op_sel_hi:[1,1,1]
	ds_read_b128 v[120:123], v65 offset:1664
	ds_read_b128 v[124:127], v65 offset:1680
	ds_read_b128 v[128:131], v65 offset:1696
	ds_read_b128 v[132:135], v65 offset:1712
	s_waitcnt lgkmcnt(8)
	v_pk_fma_f32 v[72:73], v[20:21], v[88:89], v[72:73] op_sel_hi:[0,1,1]
	v_pk_fma_f32 v[74:75], v[20:21], v[90:91], v[74:75] op_sel_hi:[0,1,1]
	v_pk_fma_f32 v[76:77], v[20:21], v[92:93], v[76:77] op_sel_hi:[0,1,1]
	v_pk_fma_f32 v[78:79], v[20:21], v[94:95], v[78:79] op_sel_hi:[0,1,1]
	v_pk_fma_f32 v[80:81], v[20:21], v[96:97], v[80:81] op_sel_hi:[0,1,1]
	v_pk_fma_f32 v[82:83], v[20:21], v[98:99], v[82:83] op_sel_hi:[0,1,1]
	v_pk_fma_f32 v[84:85], v[20:21], v[100:101], v[84:85] op_sel_hi:[0,1,1]
	v_pk_fma_f32 v[86:87], v[20:21], v[102:103], v[86:87] op_sel_hi:[0,1,1]
	ds_read_b128 v[88:91], v65 offset:1728
	ds_read_b128 v[92:95], v65 offset:1744
	ds_read_b128 v[96:99], v65 offset:1760
	ds_read_b128 v[100:103], v65 offset:1776
	s_waitcnt lgkmcnt(8)
	v_pk_fma_f32 v[72:73], v[20:21], v[104:105], v[72:73] op_sel:[1,0,0] op_sel_hi:[1,1,1]
	v_pk_fma_f32 v[74:75], v[20:21], v[106:107], v[74:75] op_sel:[1,0,0] op_sel_hi:[1,1,1]
	v_pk_fma_f32 v[76:77], v[20:21], v[108:109], v[76:77] op_sel:[1,0,0] op_sel_hi:[1,1,1]
	v_pk_fma_f32 v[78:79], v[20:21], v[110:111], v[78:79] op_sel:[1,0,0] op_sel_hi:[1,1,1]
	v_pk_fma_f32 v[80:81], v[20:21], v[112:113], v[80:81] op_sel:[1,0,0] op_sel_hi:[1,1,1]
	v_pk_fma_f32 v[82:83], v[20:21], v[114:115], v[82:83] op_sel:[1,0,0] op_sel_hi:[1,1,1]
	v_pk_fma_f32 v[84:85], v[20:21], v[116:117], v[84:85] op_sel:[1,0,0] op_sel_hi:[1,1,1]
	v_pk_fma_f32 v[86:87], v[20:21], v[118:119], v[86:87] op_sel:[1,0,0] op_sel_hi:[1,1,1]
	ds_read_b128 v[104:107], v65 offset:1792
	ds_read_b128 v[108:111], v65 offset:1808
	ds_read_b128 v[112:115], v65 offset:1824
	ds_read_b128 v[116:119], v65 offset:1840
	s_waitcnt lgkmcnt(8)
	v_pk_fma_f32 v[72:73], v[22:23], v[120:121], v[72:73] op_sel_hi:[0,1,1]
	v_pk_fma_f32 v[74:75], v[22:23], v[122:123], v[74:75] op_sel_hi:[0,1,1]
	v_pk_fma_f32 v[76:77], v[22:23], v[124:125], v[76:77] op_sel_hi:[0,1,1]
	v_pk_fma_f32 v[78:79], v[22:23], v[126:127], v[78:79] op_sel_hi:[0,1,1]
	v_pk_fma_f32 v[80:81], v[22:23], v[128:129], v[80:81] op_sel_hi:[0,1,1]
	v_pk_fma_f32 v[82:83], v[22:23], v[130:131], v[82:83] op_sel_hi:[0,1,1]
	v_pk_fma_f32 v[84:85], v[22:23], v[132:133], v[84:85] op_sel_hi:[0,1,1]
	v_pk_fma_f32 v[86:87], v[22:23], v[134:135], v[86:87] op_sel_hi:[0,1,1]
	ds_read_b128 v[120:123], v65 offset:1856
	ds_read_b128 v[124:127], v65 offset:1872
	ds_read_b128 v[128:131], v65 offset:1888
	ds_read_b128 v[132:135], v65 offset:1904
	s_waitcnt lgkmcnt(8)
	v_pk_fma_f32 v[72:73], v[22:23], v[88:89], v[72:73] op_sel:[1,0,0] op_sel_hi:[1,1,1]
	v_pk_fma_f32 v[74:75], v[22:23], v[90:91], v[74:75] op_sel:[1,0,0] op_sel_hi:[1,1,1]
	v_pk_fma_f32 v[76:77], v[22:23], v[92:93], v[76:77] op_sel:[1,0,0] op_sel_hi:[1,1,1]
	v_pk_fma_f32 v[78:79], v[22:23], v[94:95], v[78:79] op_sel:[1,0,0] op_sel_hi:[1,1,1]
	v_pk_fma_f32 v[80:81], v[22:23], v[96:97], v[80:81] op_sel:[1,0,0] op_sel_hi:[1,1,1]
	v_pk_fma_f32 v[82:83], v[22:23], v[98:99], v[82:83] op_sel:[1,0,0] op_sel_hi:[1,1,1]
	v_pk_fma_f32 v[84:85], v[22:23], v[100:101], v[84:85] op_sel:[1,0,0] op_sel_hi:[1,1,1]
	v_pk_fma_f32 v[86:87], v[22:23], v[102:103], v[86:87] op_sel:[1,0,0] op_sel_hi:[1,1,1]
	ds_read_b128 v[88:91], v65 offset:1920
	ds_read_b128 v[92:95], v65 offset:1936
	ds_read_b128 v[96:99], v65 offset:1952
	ds_read_b128 v[100:103], v65 offset:1968
	s_waitcnt lgkmcnt(8)
	v_pk_fma_f32 v[72:73], v[16:17], v[104:105], v[72:73] op_sel_hi:[0,1,1]
	v_pk_fma_f32 v[74:75], v[16:17], v[106:107], v[74:75] op_sel_hi:[0,1,1]
	v_pk_fma_f32 v[76:77], v[16:17], v[108:109], v[76:77] op_sel_hi:[0,1,1]
	v_pk_fma_f32 v[78:79], v[16:17], v[110:111], v[78:79] op_sel_hi:[0,1,1]
	v_pk_fma_f32 v[80:81], v[16:17], v[112:113], v[80:81] op_sel_hi:[0,1,1]
	v_pk_fma_f32 v[82:83], v[16:17], v[114:115], v[82:83] op_sel_hi:[0,1,1]
	v_pk_fma_f32 v[84:85], v[16:17], v[116:117], v[84:85] op_sel_hi:[0,1,1]
	v_pk_fma_f32 v[86:87], v[16:17], v[118:119], v[86:87] op_sel_hi:[0,1,1]
	ds_read_b128 v[104:107], v65 offset:1984
	ds_read_b128 v[108:111], v65 offset:2000
	ds_read_b128 v[112:115], v65 offset:2016
	ds_read_b128 v[116:119], v65 offset:2032
	s_waitcnt lgkmcnt(8)
	v_pk_fma_f32 v[72:73], v[16:17], v[120:121], v[72:73] op_sel:[1,0,0] op_sel_hi:[1,1,1]
	v_pk_fma_f32 v[74:75], v[16:17], v[122:123], v[74:75] op_sel:[1,0,0] op_sel_hi:[1,1,1]
	v_pk_fma_f32 v[76:77], v[16:17], v[124:125], v[76:77] op_sel:[1,0,0] op_sel_hi:[1,1,1]
	v_pk_fma_f32 v[78:79], v[16:17], v[126:127], v[78:79] op_sel:[1,0,0] op_sel_hi:[1,1,1]
	v_pk_fma_f32 v[80:81], v[16:17], v[128:129], v[80:81] op_sel:[1,0,0] op_sel_hi:[1,1,1]
	v_pk_fma_f32 v[82:83], v[16:17], v[130:131], v[82:83] op_sel:[1,0,0] op_sel_hi:[1,1,1]
	v_pk_fma_f32 v[84:85], v[16:17], v[132:133], v[84:85] op_sel:[1,0,0] op_sel_hi:[1,1,1]
	v_pk_fma_f32 v[86:87], v[16:17], v[134:135], v[86:87] op_sel:[1,0,0] op_sel_hi:[1,1,1]
	ds_read_b128 v[120:123], v65 offset:2048
	ds_read_b128 v[124:127], v65 offset:2064
	ds_read_b128 v[128:131], v65 offset:2080
	ds_read_b128 v[132:135], v65 offset:2096
	s_waitcnt lgkmcnt(8)
	v_pk_fma_f32 v[72:73], v[18:19], v[88:89], v[72:73] op_sel_hi:[0,1,1]
	v_pk_fma_f32 v[74:75], v[18:19], v[90:91], v[74:75] op_sel_hi:[0,1,1]
	v_pk_fma_f32 v[76:77], v[18:19], v[92:93], v[76:77] op_sel_hi:[0,1,1]
	v_pk_fma_f32 v[78:79], v[18:19], v[94:95], v[78:79] op_sel_hi:[0,1,1]
	v_pk_fma_f32 v[80:81], v[18:19], v[96:97], v[80:81] op_sel_hi:[0,1,1]
	v_pk_fma_f32 v[82:83], v[18:19], v[98:99], v[82:83] op_sel_hi:[0,1,1]
	v_pk_fma_f32 v[84:85], v[18:19], v[100:101], v[84:85] op_sel_hi:[0,1,1]
	v_pk_fma_f32 v[86:87], v[18:19], v[102:103], v[86:87] op_sel_hi:[0,1,1]
	ds_read_b128 v[88:91], v65 offset:2112
	ds_read_b128 v[92:95], v65 offset:2128
	ds_read_b128 v[96:99], v65 offset:2144
	ds_read_b128 v[100:103], v65 offset:2160
	s_waitcnt lgkmcnt(8)
	v_pk_fma_f32 v[72:73], v[18:19], v[104:105], v[72:73] op_sel:[1,0,0] op_sel_hi:[1,1,1]
	v_pk_fma_f32 v[74:75], v[18:19], v[106:107], v[74:75] op_sel:[1,0,0] op_sel_hi:[1,1,1]
	v_pk_fma_f32 v[76:77], v[18:19], v[108:109], v[76:77] op_sel:[1,0,0] op_sel_hi:[1,1,1]
	v_pk_fma_f32 v[78:79], v[18:19], v[110:111], v[78:79] op_sel:[1,0,0] op_sel_hi:[1,1,1]
	v_pk_fma_f32 v[80:81], v[18:19], v[112:113], v[80:81] op_sel:[1,0,0] op_sel_hi:[1,1,1]
	v_pk_fma_f32 v[82:83], v[18:19], v[114:115], v[82:83] op_sel:[1,0,0] op_sel_hi:[1,1,1]
	v_pk_fma_f32 v[84:85], v[18:19], v[116:117], v[84:85] op_sel:[1,0,0] op_sel_hi:[1,1,1]
	v_pk_fma_f32 v[86:87], v[18:19], v[118:119], v[86:87] op_sel:[1,0,0] op_sel_hi:[1,1,1]
	ds_read_b128 v[104:107], v65 offset:2176
	ds_read_b128 v[108:111], v65 offset:2192
	ds_read_b128 v[112:115], v65 offset:2208
	ds_read_b128 v[116:119], v65 offset:2224
	s_waitcnt lgkmcnt(8)
	v_pk_fma_f32 v[72:73], v[44:45], v[120:121], v[72:73] op_sel_hi:[0,1,1]
	v_pk_fma_f32 v[74:75], v[44:45], v[122:123], v[74:75] op_sel_hi:[0,1,1]
	v_pk_fma_f32 v[76:77], v[44:45], v[124:125], v[76:77] op_sel_hi:[0,1,1]
	v_pk_fma_f32 v[78:79], v[44:45], v[126:127], v[78:79] op_sel_hi:[0,1,1]
	v_pk_fma_f32 v[80:81], v[44:45], v[128:129], v[80:81] op_sel_hi:[0,1,1]
	v_pk_fma_f32 v[82:83], v[44:45], v[130:131], v[82:83] op_sel_hi:[0,1,1]
	v_pk_fma_f32 v[84:85], v[44:45], v[132:133], v[84:85] op_sel_hi:[0,1,1]
	v_pk_fma_f32 v[86:87], v[44:45], v[134:135], v[86:87] op_sel_hi:[0,1,1]
	ds_read_b128 v[120:123], v65 offset:2240
	ds_read_b128 v[124:127], v65 offset:2256
	ds_read_b128 v[128:131], v65 offset:2272
	ds_read_b128 v[132:135], v65 offset:2288
	s_waitcnt lgkmcnt(8)
	v_pk_fma_f32 v[72:73], v[44:45], v[88:89], v[72:73] op_sel:[1,0,0] op_sel_hi:[1,1,1]
	v_pk_fma_f32 v[74:75], v[44:45], v[90:91], v[74:75] op_sel:[1,0,0] op_sel_hi:[1,1,1]
	v_pk_fma_f32 v[76:77], v[44:45], v[92:93], v[76:77] op_sel:[1,0,0] op_sel_hi:[1,1,1]
	v_pk_fma_f32 v[78:79], v[44:45], v[94:95], v[78:79] op_sel:[1,0,0] op_sel_hi:[1,1,1]
	v_pk_fma_f32 v[80:81], v[44:45], v[96:97], v[80:81] op_sel:[1,0,0] op_sel_hi:[1,1,1]
	v_pk_fma_f32 v[82:83], v[44:45], v[98:99], v[82:83] op_sel:[1,0,0] op_sel_hi:[1,1,1]
	v_pk_fma_f32 v[84:85], v[44:45], v[100:101], v[84:85] op_sel:[1,0,0] op_sel_hi:[1,1,1]
	v_pk_fma_f32 v[86:87], v[44:45], v[102:103], v[86:87] op_sel:[1,0,0] op_sel_hi:[1,1,1]
	ds_read_b128 v[88:91], v65 offset:2304
	ds_read_b128 v[92:95], v65 offset:2320
	ds_read_b128 v[96:99], v65 offset:2336
	ds_read_b128 v[100:103], v65 offset:2352
	s_waitcnt lgkmcnt(8)
	v_pk_fma_f32 v[72:73], v[46:47], v[104:105], v[72:73] op_sel_hi:[0,1,1]
	v_pk_fma_f32 v[74:75], v[46:47], v[106:107], v[74:75] op_sel_hi:[0,1,1]
	v_pk_fma_f32 v[76:77], v[46:47], v[108:109], v[76:77] op_sel_hi:[0,1,1]
	v_pk_fma_f32 v[78:79], v[46:47], v[110:111], v[78:79] op_sel_hi:[0,1,1]
	v_pk_fma_f32 v[80:81], v[46:47], v[112:113], v[80:81] op_sel_hi:[0,1,1]
	v_pk_fma_f32 v[82:83], v[46:47], v[114:115], v[82:83] op_sel_hi:[0,1,1]
	v_pk_fma_f32 v[84:85], v[46:47], v[116:117], v[84:85] op_sel_hi:[0,1,1]
	v_pk_fma_f32 v[86:87], v[46:47], v[118:119], v[86:87] op_sel_hi:[0,1,1]
	ds_read_b128 v[104:107], v65 offset:2368
	ds_read_b128 v[108:111], v65 offset:2384
	ds_read_b128 v[112:115], v65 offset:2400
	ds_read_b128 v[116:119], v65 offset:2416
	s_waitcnt lgkmcnt(8)
	v_pk_fma_f32 v[72:73], v[46:47], v[120:121], v[72:73] op_sel:[1,0,0] op_sel_hi:[1,1,1]
	v_pk_fma_f32 v[74:75], v[46:47], v[122:123], v[74:75] op_sel:[1,0,0] op_sel_hi:[1,1,1]
	v_pk_fma_f32 v[76:77], v[46:47], v[124:125], v[76:77] op_sel:[1,0,0] op_sel_hi:[1,1,1]
	v_pk_fma_f32 v[78:79], v[46:47], v[126:127], v[78:79] op_sel:[1,0,0] op_sel_hi:[1,1,1]
	v_pk_fma_f32 v[80:81], v[46:47], v[128:129], v[80:81] op_sel:[1,0,0] op_sel_hi:[1,1,1]
	v_pk_fma_f32 v[82:83], v[46:47], v[130:131], v[82:83] op_sel:[1,0,0] op_sel_hi:[1,1,1]
	v_pk_fma_f32 v[84:85], v[46:47], v[132:133], v[84:85] op_sel:[1,0,0] op_sel_hi:[1,1,1]
	v_pk_fma_f32 v[86:87], v[46:47], v[134:135], v[86:87] op_sel:[1,0,0] op_sel_hi:[1,1,1]
	ds_read_b128 v[120:123], v65 offset:2432
	ds_read_b128 v[124:127], v65 offset:2448
	ds_read_b128 v[128:131], v65 offset:2464
	ds_read_b128 v[132:135], v65 offset:2480
	s_waitcnt lgkmcnt(8)
	v_pk_fma_f32 v[72:73], v[40:41], v[88:89], v[72:73] op_sel_hi:[0,1,1]
	v_pk_fma_f32 v[74:75], v[40:41], v[90:91], v[74:75] op_sel_hi:[0,1,1]
	v_pk_fma_f32 v[76:77], v[40:41], v[92:93], v[76:77] op_sel_hi:[0,1,1]
	v_pk_fma_f32 v[78:79], v[40:41], v[94:95], v[78:79] op_sel_hi:[0,1,1]
	v_pk_fma_f32 v[80:81], v[40:41], v[96:97], v[80:81] op_sel_hi:[0,1,1]
	v_pk_fma_f32 v[82:83], v[40:41], v[98:99], v[82:83] op_sel_hi:[0,1,1]
	v_pk_fma_f32 v[84:85], v[40:41], v[100:101], v[84:85] op_sel_hi:[0,1,1]
	v_pk_fma_f32 v[86:87], v[40:41], v[102:103], v[86:87] op_sel_hi:[0,1,1]
	ds_read_b128 v[88:91], v65 offset:2496
	ds_read_b128 v[92:95], v65 offset:2512
	ds_read_b128 v[96:99], v65 offset:2528
	ds_read_b128 v[100:103], v65 offset:2544
	s_waitcnt lgkmcnt(8)
	v_pk_fma_f32 v[72:73], v[40:41], v[104:105], v[72:73] op_sel:[1,0,0] op_sel_hi:[1,1,1]
	v_pk_fma_f32 v[74:75], v[40:41], v[106:107], v[74:75] op_sel:[1,0,0] op_sel_hi:[1,1,1]
	v_pk_fma_f32 v[76:77], v[40:41], v[108:109], v[76:77] op_sel:[1,0,0] op_sel_hi:[1,1,1]
	v_pk_fma_f32 v[78:79], v[40:41], v[110:111], v[78:79] op_sel:[1,0,0] op_sel_hi:[1,1,1]
	v_pk_fma_f32 v[80:81], v[40:41], v[112:113], v[80:81] op_sel:[1,0,0] op_sel_hi:[1,1,1]
	v_pk_fma_f32 v[82:83], v[40:41], v[114:115], v[82:83] op_sel:[1,0,0] op_sel_hi:[1,1,1]
	v_pk_fma_f32 v[84:85], v[40:41], v[116:117], v[84:85] op_sel:[1,0,0] op_sel_hi:[1,1,1]
	v_pk_fma_f32 v[86:87], v[40:41], v[118:119], v[86:87] op_sel:[1,0,0] op_sel_hi:[1,1,1]
	ds_read_b128 v[104:107], v65 offset:2560
	ds_read_b128 v[108:111], v65 offset:2576
	ds_read_b128 v[112:115], v65 offset:2592
	ds_read_b128 v[116:119], v65 offset:2608
	s_waitcnt lgkmcnt(8)
	v_pk_fma_f32 v[72:73], v[42:43], v[120:121], v[72:73] op_sel_hi:[0,1,1]
	v_pk_fma_f32 v[74:75], v[42:43], v[122:123], v[74:75] op_sel_hi:[0,1,1]
	v_pk_fma_f32 v[76:77], v[42:43], v[124:125], v[76:77] op_sel_hi:[0,1,1]
	v_pk_fma_f32 v[78:79], v[42:43], v[126:127], v[78:79] op_sel_hi:[0,1,1]
	v_pk_fma_f32 v[80:81], v[42:43], v[128:129], v[80:81] op_sel_hi:[0,1,1]
	v_pk_fma_f32 v[82:83], v[42:43], v[130:131], v[82:83] op_sel_hi:[0,1,1]
	v_pk_fma_f32 v[84:85], v[42:43], v[132:133], v[84:85] op_sel_hi:[0,1,1]
	v_pk_fma_f32 v[86:87], v[42:43], v[134:135], v[86:87] op_sel_hi:[0,1,1]
	ds_read_b128 v[120:123], v65 offset:2624
	ds_read_b128 v[124:127], v65 offset:2640
	ds_read_b128 v[128:131], v65 offset:2656
	ds_read_b128 v[132:135], v65 offset:2672
	s_waitcnt lgkmcnt(8)
	v_pk_fma_f32 v[72:73], v[42:43], v[88:89], v[72:73] op_sel:[1,0,0] op_sel_hi:[1,1,1]
	v_pk_fma_f32 v[74:75], v[42:43], v[90:91], v[74:75] op_sel:[1,0,0] op_sel_hi:[1,1,1]
	v_pk_fma_f32 v[76:77], v[42:43], v[92:93], v[76:77] op_sel:[1,0,0] op_sel_hi:[1,1,1]
	v_pk_fma_f32 v[78:79], v[42:43], v[94:95], v[78:79] op_sel:[1,0,0] op_sel_hi:[1,1,1]
	v_pk_fma_f32 v[80:81], v[42:43], v[96:97], v[80:81] op_sel:[1,0,0] op_sel_hi:[1,1,1]
	v_pk_fma_f32 v[82:83], v[42:43], v[98:99], v[82:83] op_sel:[1,0,0] op_sel_hi:[1,1,1]
	v_pk_fma_f32 v[84:85], v[42:43], v[100:101], v[84:85] op_sel:[1,0,0] op_sel_hi:[1,1,1]
	v_pk_fma_f32 v[86:87], v[42:43], v[102:103], v[86:87] op_sel:[1,0,0] op_sel_hi:[1,1,1]
	ds_read_b128 v[88:91], v65 offset:2688
	ds_read_b128 v[92:95], v65 offset:2704
	ds_read_b128 v[96:99], v65 offset:2720
	ds_read_b128 v[100:103], v65 offset:2736
	s_waitcnt lgkmcnt(8)
	v_pk_fma_f32 v[72:73], v[36:37], v[104:105], v[72:73] op_sel_hi:[0,1,1]
	v_pk_fma_f32 v[74:75], v[36:37], v[106:107], v[74:75] op_sel_hi:[0,1,1]
	v_pk_fma_f32 v[76:77], v[36:37], v[108:109], v[76:77] op_sel_hi:[0,1,1]
	v_pk_fma_f32 v[78:79], v[36:37], v[110:111], v[78:79] op_sel_hi:[0,1,1]
	v_pk_fma_f32 v[80:81], v[36:37], v[112:113], v[80:81] op_sel_hi:[0,1,1]
	v_pk_fma_f32 v[82:83], v[36:37], v[114:115], v[82:83] op_sel_hi:[0,1,1]
	v_pk_fma_f32 v[84:85], v[36:37], v[116:117], v[84:85] op_sel_hi:[0,1,1]
	v_pk_fma_f32 v[86:87], v[36:37], v[118:119], v[86:87] op_sel_hi:[0,1,1]
	ds_read_b128 v[104:107], v65 offset:2752
	ds_read_b128 v[108:111], v65 offset:2768
	ds_read_b128 v[112:115], v65 offset:2784
	ds_read_b128 v[116:119], v65 offset:2800
	s_waitcnt lgkmcnt(8)
	v_pk_fma_f32 v[72:73], v[36:37], v[120:121], v[72:73] op_sel:[1,0,0] op_sel_hi:[1,1,1]
	v_pk_fma_f32 v[74:75], v[36:37], v[122:123], v[74:75] op_sel:[1,0,0] op_sel_hi:[1,1,1]
	v_pk_fma_f32 v[76:77], v[36:37], v[124:125], v[76:77] op_sel:[1,0,0] op_sel_hi:[1,1,1]
	v_pk_fma_f32 v[78:79], v[36:37], v[126:127], v[78:79] op_sel:[1,0,0] op_sel_hi:[1,1,1]
	v_pk_fma_f32 v[80:81], v[36:37], v[128:129], v[80:81] op_sel:[1,0,0] op_sel_hi:[1,1,1]
	v_pk_fma_f32 v[82:83], v[36:37], v[130:131], v[82:83] op_sel:[1,0,0] op_sel_hi:[1,1,1]
	v_pk_fma_f32 v[84:85], v[36:37], v[132:133], v[84:85] op_sel:[1,0,0] op_sel_hi:[1,1,1]
	v_pk_fma_f32 v[86:87], v[36:37], v[134:135], v[86:87] op_sel:[1,0,0] op_sel_hi:[1,1,1]
	ds_read_b128 v[120:123], v65 offset:2816
	ds_read_b128 v[124:127], v65 offset:2832
	ds_read_b128 v[128:131], v65 offset:2848
	ds_read_b128 v[132:135], v65 offset:2864
	s_waitcnt lgkmcnt(8)
	v_pk_fma_f32 v[72:73], v[38:39], v[88:89], v[72:73] op_sel_hi:[0,1,1]
	v_pk_fma_f32 v[74:75], v[38:39], v[90:91], v[74:75] op_sel_hi:[0,1,1]
	v_pk_fma_f32 v[76:77], v[38:39], v[92:93], v[76:77] op_sel_hi:[0,1,1]
	v_pk_fma_f32 v[78:79], v[38:39], v[94:95], v[78:79] op_sel_hi:[0,1,1]
	v_pk_fma_f32 v[80:81], v[38:39], v[96:97], v[80:81] op_sel_hi:[0,1,1]
	v_pk_fma_f32 v[82:83], v[38:39], v[98:99], v[82:83] op_sel_hi:[0,1,1]
	v_pk_fma_f32 v[84:85], v[38:39], v[100:101], v[84:85] op_sel_hi:[0,1,1]
	v_pk_fma_f32 v[86:87], v[38:39], v[102:103], v[86:87] op_sel_hi:[0,1,1]
	ds_read_b128 v[88:91], v65 offset:2880
	ds_read_b128 v[92:95], v65 offset:2896
	ds_read_b128 v[96:99], v65 offset:2912
	ds_read_b128 v[100:103], v65 offset:2928
	s_waitcnt lgkmcnt(8)
	v_pk_fma_f32 v[72:73], v[38:39], v[104:105], v[72:73] op_sel:[1,0,0] op_sel_hi:[1,1,1]
	v_pk_fma_f32 v[74:75], v[38:39], v[106:107], v[74:75] op_sel:[1,0,0] op_sel_hi:[1,1,1]
	v_pk_fma_f32 v[76:77], v[38:39], v[108:109], v[76:77] op_sel:[1,0,0] op_sel_hi:[1,1,1]
	v_pk_fma_f32 v[78:79], v[38:39], v[110:111], v[78:79] op_sel:[1,0,0] op_sel_hi:[1,1,1]
	v_pk_fma_f32 v[80:81], v[38:39], v[112:113], v[80:81] op_sel:[1,0,0] op_sel_hi:[1,1,1]
	v_pk_fma_f32 v[82:83], v[38:39], v[114:115], v[82:83] op_sel:[1,0,0] op_sel_hi:[1,1,1]
	v_pk_fma_f32 v[84:85], v[38:39], v[116:117], v[84:85] op_sel:[1,0,0] op_sel_hi:[1,1,1]
	v_pk_fma_f32 v[86:87], v[38:39], v[118:119], v[86:87] op_sel:[1,0,0] op_sel_hi:[1,1,1]
	ds_read_b128 v[104:107], v65 offset:2944
	ds_read_b128 v[108:111], v65 offset:2960
	ds_read_b128 v[112:115], v65 offset:2976
	ds_read_b128 v[116:119], v65 offset:2992
	s_waitcnt lgkmcnt(8)
	v_pk_fma_f32 v[72:73], v[32:33], v[120:121], v[72:73] op_sel_hi:[0,1,1]
	v_pk_fma_f32 v[74:75], v[32:33], v[122:123], v[74:75] op_sel_hi:[0,1,1]
	v_pk_fma_f32 v[76:77], v[32:33], v[124:125], v[76:77] op_sel_hi:[0,1,1]
	v_pk_fma_f32 v[78:79], v[32:33], v[126:127], v[78:79] op_sel_hi:[0,1,1]
	v_pk_fma_f32 v[80:81], v[32:33], v[128:129], v[80:81] op_sel_hi:[0,1,1]
	v_pk_fma_f32 v[82:83], v[32:33], v[130:131], v[82:83] op_sel_hi:[0,1,1]
	v_pk_fma_f32 v[84:85], v[32:33], v[132:133], v[84:85] op_sel_hi:[0,1,1]
	v_pk_fma_f32 v[86:87], v[32:33], v[134:135], v[86:87] op_sel_hi:[0,1,1]
	ds_read_b128 v[120:123], v65 offset:3008
	ds_read_b128 v[124:127], v65 offset:3024
	ds_read_b128 v[128:131], v65 offset:3040
	ds_read_b128 v[132:135], v65 offset:3056
	s_waitcnt lgkmcnt(8)
	v_pk_fma_f32 v[72:73], v[32:33], v[88:89], v[72:73] op_sel:[1,0,0] op_sel_hi:[1,1,1]
	v_pk_fma_f32 v[74:75], v[32:33], v[90:91], v[74:75] op_sel:[1,0,0] op_sel_hi:[1,1,1]
	v_pk_fma_f32 v[76:77], v[32:33], v[92:93], v[76:77] op_sel:[1,0,0] op_sel_hi:[1,1,1]
	v_pk_fma_f32 v[78:79], v[32:33], v[94:95], v[78:79] op_sel:[1,0,0] op_sel_hi:[1,1,1]
	v_pk_fma_f32 v[80:81], v[32:33], v[96:97], v[80:81] op_sel:[1,0,0] op_sel_hi:[1,1,1]
	v_pk_fma_f32 v[82:83], v[32:33], v[98:99], v[82:83] op_sel:[1,0,0] op_sel_hi:[1,1,1]
	v_pk_fma_f32 v[84:85], v[32:33], v[100:101], v[84:85] op_sel:[1,0,0] op_sel_hi:[1,1,1]
	v_pk_fma_f32 v[86:87], v[32:33], v[102:103], v[86:87] op_sel:[1,0,0] op_sel_hi:[1,1,1]
	ds_read_b128 v[88:91], v65 offset:3072
	ds_read_b128 v[92:95], v65 offset:3088
	ds_read_b128 v[96:99], v65 offset:3104
	ds_read_b128 v[100:103], v65 offset:3120
	s_waitcnt lgkmcnt(8)
	v_pk_fma_f32 v[72:73], v[34:35], v[104:105], v[72:73] op_sel_hi:[0,1,1]
	v_pk_fma_f32 v[74:75], v[34:35], v[106:107], v[74:75] op_sel_hi:[0,1,1]
	v_pk_fma_f32 v[76:77], v[34:35], v[108:109], v[76:77] op_sel_hi:[0,1,1]
	v_pk_fma_f32 v[78:79], v[34:35], v[110:111], v[78:79] op_sel_hi:[0,1,1]
	v_pk_fma_f32 v[80:81], v[34:35], v[112:113], v[80:81] op_sel_hi:[0,1,1]
	v_pk_fma_f32 v[82:83], v[34:35], v[114:115], v[82:83] op_sel_hi:[0,1,1]
	v_pk_fma_f32 v[84:85], v[34:35], v[116:117], v[84:85] op_sel_hi:[0,1,1]
	v_pk_fma_f32 v[86:87], v[34:35], v[118:119], v[86:87] op_sel_hi:[0,1,1]
	ds_read_b128 v[104:107], v65 offset:3136
	ds_read_b128 v[108:111], v65 offset:3152
	ds_read_b128 v[112:115], v65 offset:3168
	ds_read_b128 v[116:119], v65 offset:3184
	s_waitcnt lgkmcnt(8)
	v_pk_fma_f32 v[72:73], v[34:35], v[120:121], v[72:73] op_sel:[1,0,0] op_sel_hi:[1,1,1]
	v_pk_fma_f32 v[74:75], v[34:35], v[122:123], v[74:75] op_sel:[1,0,0] op_sel_hi:[1,1,1]
	v_pk_fma_f32 v[76:77], v[34:35], v[124:125], v[76:77] op_sel:[1,0,0] op_sel_hi:[1,1,1]
	v_pk_fma_f32 v[78:79], v[34:35], v[126:127], v[78:79] op_sel:[1,0,0] op_sel_hi:[1,1,1]
	v_pk_fma_f32 v[80:81], v[34:35], v[128:129], v[80:81] op_sel:[1,0,0] op_sel_hi:[1,1,1]
	v_pk_fma_f32 v[82:83], v[34:35], v[130:131], v[82:83] op_sel:[1,0,0] op_sel_hi:[1,1,1]
	v_pk_fma_f32 v[84:85], v[34:35], v[132:133], v[84:85] op_sel:[1,0,0] op_sel_hi:[1,1,1]
	v_pk_fma_f32 v[86:87], v[34:35], v[134:135], v[86:87] op_sel:[1,0,0] op_sel_hi:[1,1,1]
	ds_read_b128 v[120:123], v65 offset:3200
	ds_read_b128 v[124:127], v65 offset:3216
	ds_read_b128 v[128:131], v65 offset:3232
	ds_read_b128 v[132:135], v65 offset:3248
	s_waitcnt lgkmcnt(8)
	v_pk_fma_f32 v[72:73], v[60:61], v[88:89], v[72:73] op_sel_hi:[0,1,1]
	v_pk_fma_f32 v[74:75], v[60:61], v[90:91], v[74:75] op_sel_hi:[0,1,1]
	v_pk_fma_f32 v[76:77], v[60:61], v[92:93], v[76:77] op_sel_hi:[0,1,1]
	v_pk_fma_f32 v[78:79], v[60:61], v[94:95], v[78:79] op_sel_hi:[0,1,1]
	v_pk_fma_f32 v[80:81], v[60:61], v[96:97], v[80:81] op_sel_hi:[0,1,1]
	v_pk_fma_f32 v[82:83], v[60:61], v[98:99], v[82:83] op_sel_hi:[0,1,1]
	v_pk_fma_f32 v[84:85], v[60:61], v[100:101], v[84:85] op_sel_hi:[0,1,1]
	v_pk_fma_f32 v[86:87], v[60:61], v[102:103], v[86:87] op_sel_hi:[0,1,1]
	ds_read_b128 v[88:91], v65 offset:3264
	ds_read_b128 v[92:95], v65 offset:3280
	ds_read_b128 v[96:99], v65 offset:3296
	ds_read_b128 v[100:103], v65 offset:3312
	s_waitcnt lgkmcnt(8)
	v_pk_fma_f32 v[72:73], v[60:61], v[104:105], v[72:73] op_sel:[1,0,0] op_sel_hi:[1,1,1]
	v_pk_fma_f32 v[74:75], v[60:61], v[106:107], v[74:75] op_sel:[1,0,0] op_sel_hi:[1,1,1]
	v_pk_fma_f32 v[76:77], v[60:61], v[108:109], v[76:77] op_sel:[1,0,0] op_sel_hi:[1,1,1]
	v_pk_fma_f32 v[78:79], v[60:61], v[110:111], v[78:79] op_sel:[1,0,0] op_sel_hi:[1,1,1]
	v_pk_fma_f32 v[80:81], v[60:61], v[112:113], v[80:81] op_sel:[1,0,0] op_sel_hi:[1,1,1]
	v_pk_fma_f32 v[82:83], v[60:61], v[114:115], v[82:83] op_sel:[1,0,0] op_sel_hi:[1,1,1]
	v_pk_fma_f32 v[84:85], v[60:61], v[116:117], v[84:85] op_sel:[1,0,0] op_sel_hi:[1,1,1]
	v_pk_fma_f32 v[86:87], v[60:61], v[118:119], v[86:87] op_sel:[1,0,0] op_sel_hi:[1,1,1]
	ds_read_b128 v[104:107], v65 offset:3328
	ds_read_b128 v[108:111], v65 offset:3344
	ds_read_b128 v[112:115], v65 offset:3360
	ds_read_b128 v[116:119], v65 offset:3376
	s_waitcnt lgkmcnt(8)
	v_pk_fma_f32 v[72:73], v[62:63], v[120:121], v[72:73] op_sel_hi:[0,1,1]
	v_pk_fma_f32 v[74:75], v[62:63], v[122:123], v[74:75] op_sel_hi:[0,1,1]
	v_pk_fma_f32 v[76:77], v[62:63], v[124:125], v[76:77] op_sel_hi:[0,1,1]
	v_pk_fma_f32 v[78:79], v[62:63], v[126:127], v[78:79] op_sel_hi:[0,1,1]
	v_pk_fma_f32 v[80:81], v[62:63], v[128:129], v[80:81] op_sel_hi:[0,1,1]
	v_pk_fma_f32 v[82:83], v[62:63], v[130:131], v[82:83] op_sel_hi:[0,1,1]
	v_pk_fma_f32 v[84:85], v[62:63], v[132:133], v[84:85] op_sel_hi:[0,1,1]
	v_pk_fma_f32 v[86:87], v[62:63], v[134:135], v[86:87] op_sel_hi:[0,1,1]
	ds_read_b128 v[120:123], v65 offset:3392
	ds_read_b128 v[124:127], v65 offset:3408
	ds_read_b128 v[128:131], v65 offset:3424
	ds_read_b128 v[132:135], v65 offset:3440
	s_waitcnt lgkmcnt(8)
	v_pk_fma_f32 v[72:73], v[62:63], v[88:89], v[72:73] op_sel:[1,0,0] op_sel_hi:[1,1,1]
	v_pk_fma_f32 v[74:75], v[62:63], v[90:91], v[74:75] op_sel:[1,0,0] op_sel_hi:[1,1,1]
	v_pk_fma_f32 v[76:77], v[62:63], v[92:93], v[76:77] op_sel:[1,0,0] op_sel_hi:[1,1,1]
	v_pk_fma_f32 v[78:79], v[62:63], v[94:95], v[78:79] op_sel:[1,0,0] op_sel_hi:[1,1,1]
	v_pk_fma_f32 v[80:81], v[62:63], v[96:97], v[80:81] op_sel:[1,0,0] op_sel_hi:[1,1,1]
	v_pk_fma_f32 v[82:83], v[62:63], v[98:99], v[82:83] op_sel:[1,0,0] op_sel_hi:[1,1,1]
	v_pk_fma_f32 v[84:85], v[62:63], v[100:101], v[84:85] op_sel:[1,0,0] op_sel_hi:[1,1,1]
	v_pk_fma_f32 v[86:87], v[62:63], v[102:103], v[86:87] op_sel:[1,0,0] op_sel_hi:[1,1,1]
	ds_read_b128 v[88:91], v65 offset:3456
	ds_read_b128 v[92:95], v65 offset:3472
	ds_read_b128 v[96:99], v65 offset:3488
	ds_read_b128 v[100:103], v65 offset:3504
	s_waitcnt lgkmcnt(8)
	v_pk_fma_f32 v[72:73], v[56:57], v[104:105], v[72:73] op_sel_hi:[0,1,1]
	v_pk_fma_f32 v[74:75], v[56:57], v[106:107], v[74:75] op_sel_hi:[0,1,1]
	v_pk_fma_f32 v[76:77], v[56:57], v[108:109], v[76:77] op_sel_hi:[0,1,1]
	v_pk_fma_f32 v[78:79], v[56:57], v[110:111], v[78:79] op_sel_hi:[0,1,1]
	v_pk_fma_f32 v[80:81], v[56:57], v[112:113], v[80:81] op_sel_hi:[0,1,1]
	v_pk_fma_f32 v[82:83], v[56:57], v[114:115], v[82:83] op_sel_hi:[0,1,1]
	v_pk_fma_f32 v[84:85], v[56:57], v[116:117], v[84:85] op_sel_hi:[0,1,1]
	v_pk_fma_f32 v[86:87], v[56:57], v[118:119], v[86:87] op_sel_hi:[0,1,1]
	ds_read_b128 v[104:107], v65 offset:3520
	ds_read_b128 v[108:111], v65 offset:3536
	ds_read_b128 v[112:115], v65 offset:3552
	ds_read_b128 v[116:119], v65 offset:3568
	s_waitcnt lgkmcnt(8)
	v_pk_fma_f32 v[72:73], v[56:57], v[120:121], v[72:73] op_sel:[1,0,0] op_sel_hi:[1,1,1]
	v_pk_fma_f32 v[74:75], v[56:57], v[122:123], v[74:75] op_sel:[1,0,0] op_sel_hi:[1,1,1]
	v_pk_fma_f32 v[76:77], v[56:57], v[124:125], v[76:77] op_sel:[1,0,0] op_sel_hi:[1,1,1]
	v_pk_fma_f32 v[78:79], v[56:57], v[126:127], v[78:79] op_sel:[1,0,0] op_sel_hi:[1,1,1]
	v_pk_fma_f32 v[80:81], v[56:57], v[128:129], v[80:81] op_sel:[1,0,0] op_sel_hi:[1,1,1]
	v_pk_fma_f32 v[82:83], v[56:57], v[130:131], v[82:83] op_sel:[1,0,0] op_sel_hi:[1,1,1]
	v_pk_fma_f32 v[84:85], v[56:57], v[132:133], v[84:85] op_sel:[1,0,0] op_sel_hi:[1,1,1]
	v_pk_fma_f32 v[86:87], v[56:57], v[134:135], v[86:87] op_sel:[1,0,0] op_sel_hi:[1,1,1]
	ds_read_b128 v[120:123], v65 offset:3584
	ds_read_b128 v[124:127], v65 offset:3600
	ds_read_b128 v[128:131], v65 offset:3616
	ds_read_b128 v[132:135], v65 offset:3632
	s_waitcnt lgkmcnt(8)
	v_pk_fma_f32 v[72:73], v[58:59], v[88:89], v[72:73] op_sel_hi:[0,1,1]
	v_pk_fma_f32 v[74:75], v[58:59], v[90:91], v[74:75] op_sel_hi:[0,1,1]
	v_pk_fma_f32 v[76:77], v[58:59], v[92:93], v[76:77] op_sel_hi:[0,1,1]
	v_pk_fma_f32 v[78:79], v[58:59], v[94:95], v[78:79] op_sel_hi:[0,1,1]
	v_pk_fma_f32 v[80:81], v[58:59], v[96:97], v[80:81] op_sel_hi:[0,1,1]
	v_pk_fma_f32 v[82:83], v[58:59], v[98:99], v[82:83] op_sel_hi:[0,1,1]
	v_pk_fma_f32 v[84:85], v[58:59], v[100:101], v[84:85] op_sel_hi:[0,1,1]
	v_pk_fma_f32 v[86:87], v[58:59], v[102:103], v[86:87] op_sel_hi:[0,1,1]
	ds_read_b128 v[88:91], v65 offset:3648
	ds_read_b128 v[92:95], v65 offset:3664
	ds_read_b128 v[96:99], v65 offset:3680
	ds_read_b128 v[100:103], v65 offset:3696
	s_waitcnt lgkmcnt(8)
	v_pk_fma_f32 v[72:73], v[58:59], v[104:105], v[72:73] op_sel:[1,0,0] op_sel_hi:[1,1,1]
	v_pk_fma_f32 v[74:75], v[58:59], v[106:107], v[74:75] op_sel:[1,0,0] op_sel_hi:[1,1,1]
	v_pk_fma_f32 v[76:77], v[58:59], v[108:109], v[76:77] op_sel:[1,0,0] op_sel_hi:[1,1,1]
	v_pk_fma_f32 v[78:79], v[58:59], v[110:111], v[78:79] op_sel:[1,0,0] op_sel_hi:[1,1,1]
	v_pk_fma_f32 v[80:81], v[58:59], v[112:113], v[80:81] op_sel:[1,0,0] op_sel_hi:[1,1,1]
	v_pk_fma_f32 v[82:83], v[58:59], v[114:115], v[82:83] op_sel:[1,0,0] op_sel_hi:[1,1,1]
	v_pk_fma_f32 v[84:85], v[58:59], v[116:117], v[84:85] op_sel:[1,0,0] op_sel_hi:[1,1,1]
	v_pk_fma_f32 v[86:87], v[58:59], v[118:119], v[86:87] op_sel:[1,0,0] op_sel_hi:[1,1,1]
	ds_read_b128 v[104:107], v65 offset:3712
	ds_read_b128 v[108:111], v65 offset:3728
	ds_read_b128 v[112:115], v65 offset:3744
	ds_read_b128 v[116:119], v65 offset:3760
	s_waitcnt lgkmcnt(8)
	v_pk_fma_f32 v[72:73], v[52:53], v[120:121], v[72:73] op_sel_hi:[0,1,1]
	v_pk_fma_f32 v[74:75], v[52:53], v[122:123], v[74:75] op_sel_hi:[0,1,1]
	v_pk_fma_f32 v[76:77], v[52:53], v[124:125], v[76:77] op_sel_hi:[0,1,1]
	v_pk_fma_f32 v[78:79], v[52:53], v[126:127], v[78:79] op_sel_hi:[0,1,1]
	v_pk_fma_f32 v[80:81], v[52:53], v[128:129], v[80:81] op_sel_hi:[0,1,1]
	v_pk_fma_f32 v[82:83], v[52:53], v[130:131], v[82:83] op_sel_hi:[0,1,1]
	v_pk_fma_f32 v[84:85], v[52:53], v[132:133], v[84:85] op_sel_hi:[0,1,1]
	v_pk_fma_f32 v[86:87], v[52:53], v[134:135], v[86:87] op_sel_hi:[0,1,1]
	ds_read_b128 v[120:123], v65 offset:3776
	ds_read_b128 v[124:127], v65 offset:3792
	ds_read_b128 v[128:131], v65 offset:3808
	ds_read_b128 v[132:135], v65 offset:3824
	s_waitcnt lgkmcnt(8)
	v_pk_fma_f32 v[72:73], v[52:53], v[88:89], v[72:73] op_sel:[1,0,0] op_sel_hi:[1,1,1]
	v_pk_fma_f32 v[74:75], v[52:53], v[90:91], v[74:75] op_sel:[1,0,0] op_sel_hi:[1,1,1]
	v_pk_fma_f32 v[76:77], v[52:53], v[92:93], v[76:77] op_sel:[1,0,0] op_sel_hi:[1,1,1]
	v_pk_fma_f32 v[78:79], v[52:53], v[94:95], v[78:79] op_sel:[1,0,0] op_sel_hi:[1,1,1]
	v_pk_fma_f32 v[80:81], v[52:53], v[96:97], v[80:81] op_sel:[1,0,0] op_sel_hi:[1,1,1]
	v_pk_fma_f32 v[82:83], v[52:53], v[98:99], v[82:83] op_sel:[1,0,0] op_sel_hi:[1,1,1]
	v_pk_fma_f32 v[84:85], v[52:53], v[100:101], v[84:85] op_sel:[1,0,0] op_sel_hi:[1,1,1]
	v_pk_fma_f32 v[86:87], v[52:53], v[102:103], v[86:87] op_sel:[1,0,0] op_sel_hi:[1,1,1]
	ds_read_b128 v[88:91], v65 offset:3840
	ds_read_b128 v[92:95], v65 offset:3856
	ds_read_b128 v[96:99], v65 offset:3872
	ds_read_b128 v[100:103], v65 offset:3888
	s_waitcnt lgkmcnt(8)
	v_pk_fma_f32 v[72:73], v[54:55], v[104:105], v[72:73] op_sel_hi:[0,1,1]
	v_pk_fma_f32 v[74:75], v[54:55], v[106:107], v[74:75] op_sel_hi:[0,1,1]
	v_pk_fma_f32 v[76:77], v[54:55], v[108:109], v[76:77] op_sel_hi:[0,1,1]
	v_pk_fma_f32 v[78:79], v[54:55], v[110:111], v[78:79] op_sel_hi:[0,1,1]
	v_pk_fma_f32 v[80:81], v[54:55], v[112:113], v[80:81] op_sel_hi:[0,1,1]
	v_pk_fma_f32 v[82:83], v[54:55], v[114:115], v[82:83] op_sel_hi:[0,1,1]
	v_pk_fma_f32 v[84:85], v[54:55], v[116:117], v[84:85] op_sel_hi:[0,1,1]
	v_pk_fma_f32 v[86:87], v[54:55], v[118:119], v[86:87] op_sel_hi:[0,1,1]
	ds_read_b128 v[104:107], v65 offset:3904
	ds_read_b128 v[108:111], v65 offset:3920
	ds_read_b128 v[112:115], v65 offset:3936
	ds_read_b128 v[116:119], v65 offset:3952
	s_waitcnt lgkmcnt(8)
	v_pk_fma_f32 v[72:73], v[54:55], v[120:121], v[72:73] op_sel:[1,0,0] op_sel_hi:[1,1,1]
	v_pk_fma_f32 v[74:75], v[54:55], v[122:123], v[74:75] op_sel:[1,0,0] op_sel_hi:[1,1,1]
	v_pk_fma_f32 v[76:77], v[54:55], v[124:125], v[76:77] op_sel:[1,0,0] op_sel_hi:[1,1,1]
	v_pk_fma_f32 v[78:79], v[54:55], v[126:127], v[78:79] op_sel:[1,0,0] op_sel_hi:[1,1,1]
	v_pk_fma_f32 v[80:81], v[54:55], v[128:129], v[80:81] op_sel:[1,0,0] op_sel_hi:[1,1,1]
	v_pk_fma_f32 v[82:83], v[54:55], v[130:131], v[82:83] op_sel:[1,0,0] op_sel_hi:[1,1,1]
	v_pk_fma_f32 v[84:85], v[54:55], v[132:133], v[84:85] op_sel:[1,0,0] op_sel_hi:[1,1,1]
	v_pk_fma_f32 v[86:87], v[54:55], v[134:135], v[86:87] op_sel:[1,0,0] op_sel_hi:[1,1,1]
	ds_read_b128 v[120:123], v65 offset:3968
	ds_read_b128 v[124:127], v65 offset:3984
	ds_read_b128 v[128:131], v65 offset:4000
	ds_read_b128 v[132:135], v65 offset:4016
	s_waitcnt lgkmcnt(8)
	v_pk_fma_f32 v[72:73], v[48:49], v[88:89], v[72:73] op_sel_hi:[0,1,1]
	v_pk_fma_f32 v[74:75], v[48:49], v[90:91], v[74:75] op_sel_hi:[0,1,1]
	v_pk_fma_f32 v[76:77], v[48:49], v[92:93], v[76:77] op_sel_hi:[0,1,1]
	v_pk_fma_f32 v[78:79], v[48:49], v[94:95], v[78:79] op_sel_hi:[0,1,1]
	v_pk_fma_f32 v[80:81], v[48:49], v[96:97], v[80:81] op_sel_hi:[0,1,1]
	v_pk_fma_f32 v[82:83], v[48:49], v[98:99], v[82:83] op_sel_hi:[0,1,1]
	v_pk_fma_f32 v[84:85], v[48:49], v[100:101], v[84:85] op_sel_hi:[0,1,1]
	v_pk_fma_f32 v[86:87], v[48:49], v[102:103], v[86:87] op_sel_hi:[0,1,1]
	ds_read_b128 v[88:91], v65 offset:4032
	ds_read_b128 v[92:95], v65 offset:4048
	ds_read_b128 v[96:99], v65 offset:4064
	ds_read_b128 v[100:103], v65 offset:4080
	s_waitcnt lgkmcnt(8)
	v_pk_fma_f32 v[72:73], v[48:49], v[104:105], v[72:73] op_sel:[1,0,0] op_sel_hi:[1,1,1]
	v_pk_fma_f32 v[74:75], v[48:49], v[106:107], v[74:75] op_sel:[1,0,0] op_sel_hi:[1,1,1]
	v_pk_fma_f32 v[76:77], v[48:49], v[108:109], v[76:77] op_sel:[1,0,0] op_sel_hi:[1,1,1]
	v_pk_fma_f32 v[78:79], v[48:49], v[110:111], v[78:79] op_sel:[1,0,0] op_sel_hi:[1,1,1]
	v_pk_fma_f32 v[80:81], v[48:49], v[112:113], v[80:81] op_sel:[1,0,0] op_sel_hi:[1,1,1]
	v_pk_fma_f32 v[82:83], v[48:49], v[114:115], v[82:83] op_sel:[1,0,0] op_sel_hi:[1,1,1]
	v_pk_fma_f32 v[84:85], v[48:49], v[116:117], v[84:85] op_sel:[1,0,0] op_sel_hi:[1,1,1]
	v_pk_fma_f32 v[86:87], v[48:49], v[118:119], v[86:87] op_sel:[1,0,0] op_sel_hi:[1,1,1]
	s_waitcnt lgkmcnt(4)
	v_pk_fma_f32 v[72:73], v[50:51], v[120:121], v[72:73] op_sel_hi:[0,1,1]
	v_pk_fma_f32 v[74:75], v[50:51], v[122:123], v[74:75] op_sel_hi:[0,1,1]
	v_pk_fma_f32 v[76:77], v[50:51], v[124:125], v[76:77] op_sel_hi:[0,1,1]
	v_pk_fma_f32 v[78:79], v[50:51], v[126:127], v[78:79] op_sel_hi:[0,1,1]
	v_pk_fma_f32 v[80:81], v[50:51], v[128:129], v[80:81] op_sel_hi:[0,1,1]
	v_pk_fma_f32 v[82:83], v[50:51], v[130:131], v[82:83] op_sel_hi:[0,1,1]
	v_pk_fma_f32 v[84:85], v[50:51], v[132:133], v[84:85] op_sel_hi:[0,1,1]
	v_pk_fma_f32 v[86:87], v[50:51], v[134:135], v[86:87] op_sel_hi:[0,1,1]
	s_waitcnt lgkmcnt(0)
	v_pk_fma_f32 v[72:73], v[50:51], v[88:89], v[72:73] op_sel:[1,0,0] op_sel_hi:[1,1,1]
	v_pk_fma_f32 v[74:75], v[50:51], v[90:91], v[74:75] op_sel:[1,0,0] op_sel_hi:[1,1,1]
	v_pk_fma_f32 v[76:77], v[50:51], v[92:93], v[76:77] op_sel:[1,0,0] op_sel_hi:[1,1,1]
	v_pk_fma_f32 v[78:79], v[50:51], v[94:95], v[78:79] op_sel:[1,0,0] op_sel_hi:[1,1,1]
	v_pk_fma_f32 v[80:81], v[50:51], v[96:97], v[80:81] op_sel:[1,0,0] op_sel_hi:[1,1,1]
	v_pk_fma_f32 v[82:83], v[50:51], v[98:99], v[82:83] op_sel:[1,0,0] op_sel_hi:[1,1,1]
	v_pk_fma_f32 v[84:85], v[50:51], v[100:101], v[84:85] op_sel:[1,0,0] op_sel_hi:[1,1,1]
	v_pk_fma_f32 v[86:87], v[50:51], v[102:103], v[86:87] op_sel:[1,0,0] op_sel_hi:[1,1,1]
	s_andn2_b64 vcc, exec, s[6:7]
	s_cbranch_vccnz .Lfold_noscale
	s_load_dwordx2 s[26:27], s[0:1], 0x80
	s_ashr_i32 s9, s8, 31
	s_lshl_b64 s[28:29], s[8:9], 2
	s_waitcnt lgkmcnt(0)
	s_add_u32 s26, s26, s28
	s_addc_u32 s27, s27, s29
	global_load_dwordx4 v[88:91], v169, s[26:27]
	global_load_dwordx4 v[92:95], v169, s[26:27] offset:16
	global_load_dwordx4 v[96:99], v169, s[26:27] offset:32
	global_load_dwordx4 v[100:103], v169, s[26:27] offset:48
	s_waitcnt vmcnt(0)
	v_pk_mul_f32 v[72:73], v[72:73], v[88:89]
	v_pk_mul_f32 v[74:75], v[74:75], v[90:91]
	v_pk_mul_f32 v[76:77], v[76:77], v[92:93]
	v_pk_mul_f32 v[78:79], v[78:79], v[94:95]
	v_pk_mul_f32 v[80:81], v[80:81], v[96:97]
	v_pk_mul_f32 v[82:83], v[82:83], v[98:99]
	v_pk_mul_f32 v[84:85], v[84:85], v[100:101]
	v_pk_mul_f32 v[86:87], v[86:87], v[102:103]
.Lfold_noscale:
	v_bfe_u32 v104, v72, 16, 1
	v_bfe_u32 v105, v73, 16, 1
	v_bfe_u32 v106, v74, 16, 1
	v_bfe_u32 v107, v75, 16, 1
	v_bfe_u32 v108, v76, 16, 1
	v_bfe_u32 v109, v77, 16, 1
	v_bfe_u32 v110, v78, 16, 1
	v_bfe_u32 v111, v79, 16, 1
	v_bfe_u32 v112, v80, 16, 1
	v_bfe_u32 v113, v81, 16, 1
	v_bfe_u32 v114, v82, 16, 1
	v_bfe_u32 v115, v83, 16, 1
	v_bfe_u32 v116, v84, 16, 1
	v_bfe_u32 v117, v85, 16, 1
	v_bfe_u32 v118, v86, 16, 1
	v_bfe_u32 v119, v87, 16, 1
	v_add3_u32 v72, v72, v104, s77
	v_add3_u32 v73, v73, v105, s77
	v_add3_u32 v74, v74, v106, s77
	v_add3_u32 v75, v75, v107, s77
	v_add3_u32 v76, v76, v108, s77
	v_add3_u32 v77, v77, v109, s77
	v_add3_u32 v78, v78, v110, s77
	v_add3_u32 v79, v79, v111, s77
	v_add3_u32 v80, v80, v112, s77
	v_add3_u32 v81, v81, v113, s77
	v_add3_u32 v82, v82, v114, s77
	v_add3_u32 v83, v83, v115, s77
	v_add3_u32 v84, v84, v116, s77
	v_add3_u32 v85, v85, v117, s77
	v_add3_u32 v86, v86, v118, s77
	v_add3_u32 v87, v87, v119, s77
	global_store_short_d16_hi v[68:69], v72, off
	s_nop 0
	v_lshl_add_u64 v[68:69], v[68:69], 0, s[36:37]
	global_store_short_d16_hi v[68:69], v73, off
	s_nop 0
	v_lshl_add_u64 v[68:69], v[68:69], 0, s[36:37]
	global_store_short_d16_hi v[68:69], v74, off
	s_nop 0
	v_lshl_add_u64 v[68:69], v[68:69], 0, s[36:37]
	global_store_short_d16_hi v[68:69], v75, off
	s_nop 0
	v_lshl_add_u64 v[68:69], v[68:69], 0, s[36:37]
	global_store_short_d16_hi v[68:69], v76, off
	s_nop 0
	v_lshl_add_u64 v[68:69], v[68:69], 0, s[36:37]
	global_store_short_d16_hi v[68:69], v77, off
	s_nop 0
	v_lshl_add_u64 v[68:69], v[68:69], 0, s[36:37]
	global_store_short_d16_hi v[68:69], v78, off
	s_nop 0
	v_lshl_add_u64 v[68:69], v[68:69], 0, s[36:37]
	global_store_short_d16_hi v[68:69], v79, off
	s_nop 0
	v_lshl_add_u64 v[68:69], v[68:69], 0, s[36:37]
	global_store_short_d16_hi v[68:69], v80, off
	s_nop 0
	v_lshl_add_u64 v[68:69], v[68:69], 0, s[36:37]
	global_store_short_d16_hi v[68:69], v81, off
	s_nop 0
	v_lshl_add_u64 v[68:69], v[68:69], 0, s[36:37]
	global_store_short_d16_hi v[68:69], v82, off
	s_nop 0
	v_lshl_add_u64 v[68:69], v[68:69], 0, s[36:37]
	global_store_short_d16_hi v[68:69], v83, off
	s_nop 0
	v_lshl_add_u64 v[68:69], v[68:69], 0, s[36:37]
	global_store_short_d16_hi v[68:69], v84, off
	s_nop 0
	v_lshl_add_u64 v[68:69], v[68:69], 0, s[36:37]
	global_store_short_d16_hi v[68:69], v85, off
	s_nop 0
	v_lshl_add_u64 v[68:69], v[68:69], 0, s[36:37]
	global_store_short_d16_hi v[68:69], v86, off
	s_nop 0
	v_lshl_add_u64 v[68:69], v[68:69], 0, s[36:37]
	global_store_short_d16_hi v[68:69], v87, off
	s_nop 0
	v_lshl_add_u64 v[68:69], v[68:69], 0, s[36:37]
	s_add_i32 s8, s8, 16
	s_mov_b64 s[10:11], 64

.LBB0_170:
	s_and_b64 vcc, exec, s[6:7]
	s_cbranch_vccz .LBB0_159
	s_add_u32 s8, s15, s23
	s_addc_u32 s9, s16, s22
	s_lshl_b32 s10, s21, 4
	s_ashr_i32 s11, s10, 31
	v_lshl_add_u64 v[12:13], s[10:11], 2, v[66:67]
	global_load_dwordx4 v[0:3], v[12:13], off offset:1536
	global_load_dwordx4 v[4:7], v[12:13], off offset:1552
	global_load_dwordx4 v[8:11], v[12:13], off offset:1568
	s_nop 0
	global_load_dwordx4 v[12:15], v[12:13], off offset:1584
	s_load_dwordx2 s[22:23], s[0:1], 0x48
	s_lshl_b32 s11, s20, 5
	s_add_i32 s24, s10, s11
	v_ashrrev_i32_e32 v65, 31, v64
	s_lshl_b32 s20, s21, 7
	s_ashr_i32 s25, s24, 31
	v_lshl_add_u64 v[16:17], v[64:65], 1, s[8:9]
	s_add_i32 s10, s20, 0x200
	s_add_i32 s11, s20, 0x202
	s_lshl_b64 s[8:9], s[24:25], 9
	s_waitcnt lgkmcnt(0)
	s_add_u32 s22, s22, s19
	s_addc_u32 s23, s23, 0
	s_add_u32 s22, s22, s8
	s_mov_b64 s[6:7], 0
	s_mov_b32 s20, s10
	s_mov_b32 s21, s11
	s_addc_u32 s23, s23, s9
	s_mov_b64 s[8:9], s[4:5]
	s_waitcnt vmcnt(0)
	v_mov_b32_e32 v18, v0
	v_mov_b32_e32 v19, v0
	v_mov_b32_e32 v0, v1
	v_mov_b32_e32 v20, v2
	v_mov_b32_e32 v21, v2
	v_mov_b32_e32 v2, v3
	v_mov_b32_e32 v22, v4
	v_mov_b32_e32 v23, v4
	v_mov_b32_e32 v4, v5
	v_mov_b32_e32 v24, v6
	v_mov_b32_e32 v25, v6
	v_mov_b32_e32 v6, v7
	v_mov_b32_e32 v26, v8
	v_mov_b32_e32 v27, v8
	v_mov_b32_e32 v8, v9
	v_mov_b32_e32 v28, v10
	v_mov_b32_e32 v29, v10
	v_mov_b32_e32 v10, v11
	v_mov_b32_e32 v30, v12
	v_mov_b32_e32 v31, v12
	v_mov_b32_e32 v12, v13
	v_mov_b32_e32 v32, v14
	v_mov_b32_e32 v33, v14
	v_mov_b32_e32 v14, v15
	s_lshl_b32 s26, s68, 6
	v_lshlrev_b32_e32 v121, 4, v70
	v_lshrrev_b32_e32 v120, 3, v70
	v_and_b32_e32 v122, 7, v70
	v_lshlrev_b32_e32 v120, 9, v120
	v_lshl_add_u32 v120, v122, 4, v120
	v_add_u32_e32 v121, s26, v121
	global_load_dwordx4 v[72:75], v120, s[22:23]
	v_add_u32_e32 v122, 0x1000, v120
	s_add_i32 s24, s10, s8
	global_load_dwordx4 v[76:79], v122, s[22:23]
	s_ashr_i32 s25, s24, 31
	s_lshl_b64 s[24:25], s[24:25], 11
	v_lshl_add_u64 v[124:125], v[16:17], 0, s[24:25]
	s_waitcnt vmcnt(0)
	ds_write_b128 v121, v[72:75]
	ds_write_b128 v121, v[76:79] offset:1024
	v_mov_b32_e32 v120, s26
	s_waitcnt lgkmcnt(0)
	ds_read_b128 v[72:75], v120 offset:0
	ds_read_b128 v[76:79], v120 offset:16
	ds_read_b128 v[80:83], v120 offset:32
	ds_read_b128 v[84:87], v120 offset:48
	ds_read_b128 v[88:91], v120 offset:64
	ds_read_b128 v[92:95], v120 offset:80
	ds_read_b128 v[96:99], v120 offset:96
	ds_read_b128 v[100:103], v120 offset:112
	ds_read_b128 v[104:107], v120 offset:128
	ds_read_b128 v[108:111], v120 offset:144
	ds_read_b128 v[112:115], v120 offset:160
	ds_read_b128 v[116:119], v120 offset:176
	s_waitcnt lgkmcnt(8)
	v_pk_mul_f32 v[34:35], v[18:19], v[72:73]
	v_pk_mul_f32 v[36:37], v[18:19], v[74:75]
	v_pk_mul_f32 v[38:39], v[18:19], v[76:77]
	v_pk_mul_f32 v[40:41], v[18:19], v[78:79]
	v_pk_mul_f32 v[42:43], v[18:19], v[80:81]
	v_pk_mul_f32 v[44:45], v[18:19], v[82:83]
	v_pk_mul_f32 v[46:47], v[18:19], v[84:85]
	v_pk_mul_f32 v[48:49], v[18:19], v[86:87]
	ds_read_b128 v[72:75], v120 offset:192
	ds_read_b128 v[76:79], v120 offset:208
	ds_read_b128 v[80:83], v120 offset:224
	ds_read_b128 v[84:87], v120 offset:240
	s_waitcnt lgkmcnt(8)
	v_pk_mul_f32 v[50:51], v[18:19], v[88:89]
	v_pk_mul_f32 v[52:53], v[18:19], v[90:91]
	v_pk_mul_f32 v[54:55], v[18:19], v[92:93]
	v_pk_mul_f32 v[56:57], v[18:19], v[94:95]
	v_pk_mul_f32 v[58:59], v[18:19], v[96:97]
	v_pk_mul_f32 v[60:61], v[18:19], v[98:99]
	v_pk_mul_f32 v[62:63], v[18:19], v[100:101]
	v_pk_mul_f32 v[64:65], v[18:19], v[102:103]
	ds_read_b128 v[88:91], v120 offset:256
	ds_read_b128 v[92:95], v120 offset:272
	ds_read_b128 v[96:99], v120 offset:288
	ds_read_b128 v[100:103], v120 offset:304
	s_waitcnt lgkmcnt(8)
	v_pk_fma_f32 v[34:35], v[0:1], v[104:105], v[34:35]
	v_pk_fma_f32 v[36:37], v[0:1], v[106:107], v[36:37]
	v_pk_fma_f32 v[38:39], v[0:1], v[108:109], v[38:39]
	v_pk_fma_f32 v[40:41], v[0:1], v[110:111], v[40:41]
	v_pk_fma_f32 v[42:43], v[0:1], v[112:113], v[42:43]
	v_pk_fma_f32 v[44:45], v[0:1], v[114:115], v[44:45]
	v_pk_fma_f32 v[46:47], v[0:1], v[116:117], v[46:47]
	v_pk_fma_f32 v[48:49], v[0:1], v[118:119], v[48:49]
	ds_read_b128 v[104:107], v120 offset:320
	ds_read_b128 v[108:111], v120 offset:336
	ds_read_b128 v[112:115], v120 offset:352
	ds_read_b128 v[116:119], v120 offset:368
	s_waitcnt lgkmcnt(8)
	v_pk_fma_f32 v[50:51], v[0:1], v[72:73], v[50:51]
	v_pk_fma_f32 v[52:53], v[0:1], v[74:75], v[52:53]
	v_pk_fma_f32 v[54:55], v[0:1], v[76:77], v[54:55]
	v_pk_fma_f32 v[56:57], v[0:1], v[78:79], v[56:57]
	v_pk_fma_f32 v[58:59], v[0:1], v[80:81], v[58:59]
	v_pk_fma_f32 v[60:61], v[0:1], v[82:83], v[60:61]
	v_pk_fma_f32 v[62:63], v[0:1], v[84:85], v[62:63]
	v_pk_fma_f32 v[64:65], v[0:1], v[86:87], v[64:65]
	ds_read_b128 v[72:75], v120 offset:384
	ds_read_b128 v[76:79], v120 offset:400
	ds_read_b128 v[80:83], v120 offset:416
	ds_read_b128 v[84:87], v120 offset:432
	s_waitcnt lgkmcnt(8)
	v_pk_fma_f32 v[34:35], v[20:21], v[88:89], v[34:35]
	v_pk_fma_f32 v[36:37], v[20:21], v[90:91], v[36:37]
	v_pk_fma_f32 v[38:39], v[20:21], v[92:93], v[38:39]
	v_pk_fma_f32 v[40:41], v[20:21], v[94:95], v[40:41]
	v_pk_fma_f32 v[42:43], v[20:21], v[96:97], v[42:43]
	v_pk_fma_f32 v[44:45], v[20:21], v[98:99], v[44:45]
	v_pk_fma_f32 v[46:47], v[20:21], v[100:101], v[46:47]
	v_pk_fma_f32 v[48:49], v[20:21], v[102:103], v[48:49]
	ds_read_b128 v[88:91], v120 offset:448
	ds_read_b128 v[92:95], v120 offset:464
	ds_read_b128 v[96:99], v120 offset:480
	ds_read_b128 v[100:103], v120 offset:496
	s_waitcnt lgkmcnt(8)
	v_pk_fma_f32 v[50:51], v[20:21], v[104:105], v[50:51]
	v_pk_fma_f32 v[52:53], v[20:21], v[106:107], v[52:53]
	v_pk_fma_f32 v[54:55], v[20:21], v[108:109], v[54:55]
	v_pk_fma_f32 v[56:57], v[20:21], v[110:111], v[56:57]
	v_pk_fma_f32 v[58:59], v[20:21], v[112:113], v[58:59]
	v_pk_fma_f32 v[60:61], v[20:21], v[114:115], v[60:61]
	v_pk_fma_f32 v[62:63], v[20:21], v[116:117], v[62:63]
	v_pk_fma_f32 v[64:65], v[20:21], v[118:119], v[64:65]
	ds_read_b128 v[104:107], v120 offset:512
	ds_read_b128 v[108:111], v120 offset:528
	ds_read_b128 v[112:115], v120 offset:544
	ds_read_b128 v[116:119], v120 offset:560
	s_waitcnt lgkmcnt(8)
	v_pk_fma_f32 v[34:35], v[2:3], v[72:73], v[34:35]
	v_pk_fma_f32 v[36:37], v[2:3], v[74:75], v[36:37]
	v_pk_fma_f32 v[38:39], v[2:3], v[76:77], v[38:39]
	v_pk_fma_f32 v[40:41], v[2:3], v[78:79], v[40:41]
	v_pk_fma_f32 v[42:43], v[2:3], v[80:81], v[42:43]
	v_pk_fma_f32 v[44:45], v[2:3], v[82:83], v[44:45]
	v_pk_fma_f32 v[46:47], v[2:3], v[84:85], v[46:47]
	v_pk_fma_f32 v[48:49], v[2:3], v[86:87], v[48:49]
	ds_read_b128 v[72:75], v120 offset:576
	ds_read_b128 v[76:79], v120 offset:592
	ds_read_b128 v[80:83], v120 offset:608
	ds_read_b128 v[84:87], v120 offset:624
	s_waitcnt lgkmcnt(8)
	v_pk_fma_f32 v[50:51], v[2:3], v[88:89], v[50:51]
	v_pk_fma_f32 v[52:53], v[2:3], v[90:91], v[52:53]
	v_pk_fma_f32 v[54:55], v[2:3], v[92:93], v[54:55]
	v_pk_fma_f32 v[56:57], v[2:3], v[94:95], v[56:57]
	v_pk_fma_f32 v[58:59], v[2:3], v[96:97], v[58:59]
	v_pk_fma_f32 v[60:61], v[2:3], v[98:99], v[60:61]
	v_pk_fma_f32 v[62:63], v[2:3], v[100:101], v[62:63]
	v_pk_fma_f32 v[64:65], v[2:3], v[102:103], v[64:65]
	ds_read_b128 v[88:91], v120 offset:640
	ds_read_b128 v[92:95], v120 offset:656
	ds_read_b128 v[96:99], v120 offset:672
	ds_read_b128 v[100:103], v120 offset:688
	s_waitcnt lgkmcnt(8)
	v_pk_fma_f32 v[34:35], v[22:23], v[104:105], v[34:35]
	v_pk_fma_f32 v[36:37], v[22:23], v[106:107], v[36:37]
	v_pk_fma_f32 v[38:39], v[22:23], v[108:109], v[38:39]
	v_pk_fma_f32 v[40:41], v[22:23], v[110:111], v[40:41]
	v_pk_fma_f32 v[42:43], v[22:23], v[112:113], v[42:43]
	v_pk_fma_f32 v[44:45], v[22:23], v[114:115], v[44:45]
	v_pk_fma_f32 v[46:47], v[22:23], v[116:117], v[46:47]
	v_pk_fma_f32 v[48:49], v[22:23], v[118:119], v[48:49]
	ds_read_b128 v[104:107], v120 offset:704
	ds_read_b128 v[108:111], v120 offset:720
	ds_read_b128 v[112:115], v120 offset:736
	ds_read_b128 v[116:119], v120 offset:752
	s_waitcnt lgkmcnt(8)
	v_pk_fma_f32 v[50:51], v[22:23], v[72:73], v[50:51]
	v_pk_fma_f32 v[52:53], v[22:23], v[74:75], v[52:53]
	v_pk_fma_f32 v[54:55], v[22:23], v[76:77], v[54:55]
	v_pk_fma_f32 v[56:57], v[22:23], v[78:79], v[56:57]
	v_pk_fma_f32 v[58:59], v[22:23], v[80:81], v[58:59]
	v_pk_fma_f32 v[60:61], v[22:23], v[82:83], v[60:61]
	v_pk_fma_f32 v[62:63], v[22:23], v[84:85], v[62:63]
	v_pk_fma_f32 v[64:65], v[22:23], v[86:87], v[64:65]
	ds_read_b128 v[72:75], v120 offset:768
	ds_read_b128 v[76:79], v120 offset:784
	ds_read_b128 v[80:83], v120 offset:800
	ds_read_b128 v[84:87], v120 offset:816
	s_waitcnt lgkmcnt(8)
	v_pk_fma_f32 v[34:35], v[4:5], v[88:89], v[34:35]
	v_pk_fma_f32 v[36:37], v[4:5], v[90:91], v[36:37]
	v_pk_fma_f32 v[38:39], v[4:5], v[92:93], v[38:39]
	v_pk_fma_f32 v[40:41], v[4:5], v[94:95], v[40:41]
	v_pk_fma_f32 v[42:43], v[4:5], v[96:97], v[42:43]
	v_pk_fma_f32 v[44:45], v[4:5], v[98:99], v[44:45]
	v_pk_fma_f32 v[46:47], v[4:5], v[100:101], v[46:47]
	v_pk_fma_f32 v[48:49], v[4:5], v[102:103], v[48:49]
	ds_read_b128 v[88:91], v120 offset:832
	ds_read_b128 v[92:95], v120 offset:848
	ds_read_b128 v[96:99], v120 offset:864
	ds_read_b128 v[100:103], v120 offset:880
	s_waitcnt lgkmcnt(8)
	v_pk_fma_f32 v[50:51], v[4:5], v[104:105], v[50:51]
	v_pk_fma_f32 v[52:53], v[4:5], v[106:107], v[52:53]
	v_pk_fma_f32 v[54:55], v[4:5], v[108:109], v[54:55]
	v_pk_fma_f32 v[56:57], v[4:5], v[110:111], v[56:57]
	v_pk_fma_f32 v[58:59], v[4:5], v[112:113], v[58:59]
	v_pk_fma_f32 v[60:61], v[4:5], v[114:115], v[60:61]
	v_pk_fma_f32 v[62:63], v[4:5], v[116:117], v[62:63]
	v_pk_fma_f32 v[64:65], v[4:5], v[118:119], v[64:65]
	ds_read_b128 v[104:107], v120 offset:896
	ds_read_b128 v[108:111], v120 offset:912
	ds_read_b128 v[112:115], v120 offset:928
	ds_read_b128 v[116:119], v120 offset:944
	s_waitcnt lgkmcnt(8)
	v_pk_fma_f32 v[34:35], v[24:25], v[72:73], v[34:35]
	v_pk_fma_f32 v[36:37], v[24:25], v[74:75], v[36:37]
	v_pk_fma_f32 v[38:39], v[24:25], v[76:77], v[38:39]
	v_pk_fma_f32 v[40:41], v[24:25], v[78:79], v[40:41]
	v_pk_fma_f32 v[42:43], v[24:25], v[80:81], v[42:43]
	v_pk_fma_f32 v[44:45], v[24:25], v[82:83], v[44:45]
	v_pk_fma_f32 v[46:47], v[24:25], v[84:85], v[46:47]
	v_pk_fma_f32 v[48:49], v[24:25], v[86:87], v[48:49]
	ds_read_b128 v[72:75], v120 offset:960
	ds_read_b128 v[76:79], v120 offset:976
	ds_read_b128 v[80:83], v120 offset:992
	ds_read_b128 v[84:87], v120 offset:1008
	s_waitcnt lgkmcnt(8)
	v_pk_fma_f32 v[50:51], v[24:25], v[88:89], v[50:51]
	v_pk_fma_f32 v[52:53], v[24:25], v[90:91], v[52:53]
	v_pk_fma_f32 v[54:55], v[24:25], v[92:93], v[54:55]
	v_pk_fma_f32 v[56:57], v[24:25], v[94:95], v[56:57]
	v_pk_fma_f32 v[58:59], v[24:25], v[96:97], v[58:59]
	v_pk_fma_f32 v[60:61], v[24:25], v[98:99], v[60:61]
	v_pk_fma_f32 v[62:63], v[24:25], v[100:101], v[62:63]
	v_pk_fma_f32 v[64:65], v[24:25], v[102:103], v[64:65]
	ds_read_b128 v[88:91], v120 offset:1024
	ds_read_b128 v[92:95], v120 offset:1040
	ds_read_b128 v[96:99], v120 offset:1056
	ds_read_b128 v[100:103], v120 offset:1072
	s_waitcnt lgkmcnt(8)
	v_pk_fma_f32 v[34:35], v[6:7], v[104:105], v[34:35]
	v_pk_fma_f32 v[36:37], v[6:7], v[106:107], v[36:37]
	v_pk_fma_f32 v[38:39], v[6:7], v[108:109], v[38:39]
	v_pk_fma_f32 v[40:41], v[6:7], v[110:111], v[40:41]
	v_pk_fma_f32 v[42:43], v[6:7], v[112:113], v[42:43]
	v_pk_fma_f32 v[44:45], v[6:7], v[114:115], v[44:45]
	v_pk_fma_f32 v[46:47], v[6:7], v[116:117], v[46:47]
	v_pk_fma_f32 v[48:49], v[6:7], v[118:119], v[48:49]
	ds_read_b128 v[104:107], v120 offset:1088
	ds_read_b128 v[108:111], v120 offset:1104
	ds_read_b128 v[112:115], v120 offset:1120
	ds_read_b128 v[116:119], v120 offset:1136
	s_waitcnt lgkmcnt(8)
	v_pk_fma_f32 v[50:51], v[6:7], v[72:73], v[50:51]
	v_pk_fma_f32 v[52:53], v[6:7], v[74:75], v[52:53]
	v_pk_fma_f32 v[54:55], v[6:7], v[76:77], v[54:55]
	v_pk_fma_f32 v[56:57], v[6:7], v[78:79], v[56:57]
	v_pk_fma_f32 v[58:59], v[6:7], v[80:81], v[58:59]
	v_pk_fma_f32 v[60:61], v[6:7], v[82:83], v[60:61]
	v_pk_fma_f32 v[62:63], v[6:7], v[84:85], v[62:63]
	v_pk_fma_f32 v[64:65], v[6:7], v[86:87], v[64:65]
	ds_read_b128 v[72:75], v120 offset:1152
	ds_read_b128 v[76:79], v120 offset:1168
	ds_read_b128 v[80:83], v120 offset:1184
	ds_read_b128 v[84:87], v120 offset:1200
	s_waitcnt lgkmcnt(8)
	v_pk_fma_f32 v[34:35], v[26:27], v[88:89], v[34:35]
	v_pk_fma_f32 v[36:37], v[26:27], v[90:91], v[36:37]
	v_pk_fma_f32 v[38:39], v[26:27], v[92:93], v[38:39]
	v_pk_fma_f32 v[40:41], v[26:27], v[94:95], v[40:41]
	v_pk_fma_f32 v[42:43], v[26:27], v[96:97], v[42:43]
	v_pk_fma_f32 v[44:45], v[26:27], v[98:99], v[44:45]
	v_pk_fma_f32 v[46:47], v[26:27], v[100:101], v[46:47]
	v_pk_fma_f32 v[48:49], v[26:27], v[102:103], v[48:49]
	ds_read_b128 v[88:91], v120 offset:1216
	ds_read_b128 v[92:95], v120 offset:1232
	ds_read_b128 v[96:99], v120 offset:1248
	ds_read_b128 v[100:103], v120 offset:1264
	s_waitcnt lgkmcnt(8)
	v_pk_fma_f32 v[50:51], v[26:27], v[104:105], v[50:51]
	v_pk_fma_f32 v[52:53], v[26:27], v[106:107], v[52:53]
	v_pk_fma_f32 v[54:55], v[26:27], v[108:109], v[54:55]
	v_pk_fma_f32 v[56:57], v[26:27], v[110:111], v[56:57]
	v_pk_fma_f32 v[58:59], v[26:27], v[112:113], v[58:59]
	v_pk_fma_f32 v[60:61], v[26:27], v[114:115], v[60:61]
	v_pk_fma_f32 v[62:63], v[26:27], v[116:117], v[62:63]
	v_pk_fma_f32 v[64:65], v[26:27], v[118:119], v[64:65]
	ds_read_b128 v[104:107], v120 offset:1280
	ds_read_b128 v[108:111], v120 offset:1296
	ds_read_b128 v[112:115], v120 offset:1312
	ds_read_b128 v[116:119], v120 offset:1328
	s_waitcnt lgkmcnt(8)
	v_pk_fma_f32 v[34:35], v[8:9], v[72:73], v[34:35]
	v_pk_fma_f32 v[36:37], v[8:9], v[74:75], v[36:37]
	v_pk_fma_f32 v[38:39], v[8:9], v[76:77], v[38:39]
	v_pk_fma_f32 v[40:41], v[8:9], v[78:79], v[40:41]
	v_pk_fma_f32 v[42:43], v[8:9], v[80:81], v[42:43]
	v_pk_fma_f32 v[44:45], v[8:9], v[82:83], v[44:45]
	v_pk_fma_f32 v[46:47], v[8:9], v[84:85], v[46:47]
	v_pk_fma_f32 v[48:49], v[8:9], v[86:87], v[48:49]
	ds_read_b128 v[72:75], v120 offset:1344
	ds_read_b128 v[76:79], v120 offset:1360
	ds_read_b128 v[80:83], v120 offset:1376
	ds_read_b128 v[84:87], v120 offset:1392
	s_waitcnt lgkmcnt(8)
	v_pk_fma_f32 v[50:51], v[8:9], v[88:89], v[50:51]
	v_pk_fma_f32 v[52:53], v[8:9], v[90:91], v[52:53]
	v_pk_fma_f32 v[54:55], v[8:9], v[92:93], v[54:55]
	v_pk_fma_f32 v[56:57], v[8:9], v[94:95], v[56:57]
	v_pk_fma_f32 v[58:59], v[8:9], v[96:97], v[58:59]
	v_pk_fma_f32 v[60:61], v[8:9], v[98:99], v[60:61]
	v_pk_fma_f32 v[62:63], v[8:9], v[100:101], v[62:63]
	v_pk_fma_f32 v[64:65], v[8:9], v[102:103], v[64:65]
	ds_read_b128 v[88:91], v120 offset:1408
	ds_read_b128 v[92:95], v120 offset:1424
	ds_read_b128 v[96:99], v120 offset:1440
	ds_read_b128 v[100:103], v120 offset:1456
	s_waitcnt lgkmcnt(8)
	v_pk_fma_f32 v[34:35], v[28:29], v[104:105], v[34:35]
	v_pk_fma_f32 v[36:37], v[28:29], v[106:107], v[36:37]
	v_pk_fma_f32 v[38:39], v[28:29], v[108:109], v[38:39]
	v_pk_fma_f32 v[40:41], v[28:29], v[110:111], v[40:41]
	v_pk_fma_f32 v[42:43], v[28:29], v[112:113], v[42:43]
	v_pk_fma_f32 v[44:45], v[28:29], v[114:115], v[44:45]
	v_pk_fma_f32 v[46:47], v[28:29], v[116:117], v[46:47]
	v_pk_fma_f32 v[48:49], v[28:29], v[118:119], v[48:49]
	ds_read_b128 v[104:107], v120 offset:1472
	ds_read_b128 v[108:111], v120 offset:1488
	ds_read_b128 v[112:115], v120 offset:1504
	ds_read_b128 v[116:119], v120 offset:1520
	s_waitcnt lgkmcnt(8)
	v_pk_fma_f32 v[50:51], v[28:29], v[72:73], v[50:51]
	v_pk_fma_f32 v[52:53], v[28:29], v[74:75], v[52:53]
	v_pk_fma_f32 v[54:55], v[28:29], v[76:77], v[54:55]
	v_pk_fma_f32 v[56:57], v[28:29], v[78:79], v[56:57]
	v_pk_fma_f32 v[58:59], v[28:29], v[80:81], v[58:59]
	v_pk_fma_f32 v[60:61], v[28:29], v[82:83], v[60:61]
	v_pk_fma_f32 v[62:63], v[28:29], v[84:85], v[62:63]
	v_pk_fma_f32 v[64:65], v[28:29], v[86:87], v[64:65]
	ds_read_b128 v[72:75], v120 offset:1536
	ds_read_b128 v[76:79], v120 offset:1552
	ds_read_b128 v[80:83], v120 offset:1568
	ds_read_b128 v[84:87], v120 offset:1584
	s_waitcnt lgkmcnt(8)
	v_pk_fma_f32 v[34:35], v[10:11], v[88:89], v[34:35]
	v_pk_fma_f32 v[36:37], v[10:11], v[90:91], v[36:37]
	v_pk_fma_f32 v[38:39], v[10:11], v[92:93], v[38:39]
	v_pk_fma_f32 v[40:41], v[10:11], v[94:95], v[40:41]
	v_pk_fma_f32 v[42:43], v[10:11], v[96:97], v[42:43]
	v_pk_fma_f32 v[44:45], v[10:11], v[98:99], v[44:45]
	v_pk_fma_f32 v[46:47], v[10:11], v[100:101], v[46:47]
	v_pk_fma_f32 v[48:49], v[10:11], v[102:103], v[48:49]
	ds_read_b128 v[88:91], v120 offset:1600
	ds_read_b128 v[92:95], v120 offset:1616
	ds_read_b128 v[96:99], v120 offset:1632
	ds_read_b128 v[100:103], v120 offset:1648
	s_waitcnt lgkmcnt(8)
	v_pk_fma_f32 v[50:51], v[10:11], v[104:105], v[50:51]
	v_pk_fma_f32 v[52:53], v[10:11], v[106:107], v[52:53]
	v_pk_fma_f32 v[54:55], v[10:11], v[108:109], v[54:55]
	v_pk_fma_f32 v[56:57], v[10:11], v[110:111], v[56:57]
	v_pk_fma_f32 v[58:59], v[10:11], v[112:113], v[58:59]
	v_pk_fma_f32 v[60:61], v[10:11], v[114:115], v[60:61]
	v_pk_fma_f32 v[62:63], v[10:11], v[116:117], v[62:63]
	v_pk_fma_f32 v[64:65], v[10:11], v[118:119], v[64:65]
	ds_read_b128 v[104:107], v120 offset:1664
	ds_read_b128 v[108:111], v120 offset:1680
	ds_read_b128 v[112:115], v120 offset:1696
	ds_read_b128 v[116:119], v120 offset:1712
	s_waitcnt lgkmcnt(8)
	v_pk_fma_f32 v[34:35], v[30:31], v[72:73], v[34:35]
	v_pk_fma_f32 v[36:37], v[30:31], v[74:75], v[36:37]
	v_pk_fma_f32 v[38:39], v[30:31], v[76:77], v[38:39]
	v_pk_fma_f32 v[40:41], v[30:31], v[78:79], v[40:41]
	v_pk_fma_f32 v[42:43], v[30:31], v[80:81], v[42:43]
	v_pk_fma_f32 v[44:45], v[30:31], v[82:83], v[44:45]
	v_pk_fma_f32 v[46:47], v[30:31], v[84:85], v[46:47]
	v_pk_fma_f32 v[48:49], v[30:31], v[86:87], v[48:49]
	ds_read_b128 v[72:75], v120 offset:1728
	ds_read_b128 v[76:79], v120 offset:1744
	ds_read_b128 v[80:83], v120 offset:1760
	ds_read_b128 v[84:87], v120 offset:1776
	s_waitcnt lgkmcnt(8)
	v_pk_fma_f32 v[50:51], v[30:31], v[88:89], v[50:51]
	v_pk_fma_f32 v[52:53], v[30:31], v[90:91], v[52:53]
	v_pk_fma_f32 v[54:55], v[30:31], v[92:93], v[54:55]
	v_pk_fma_f32 v[56:57], v[30:31], v[94:95], v[56:57]
	v_pk_fma_f32 v[58:59], v[30:31], v[96:97], v[58:59]
	v_pk_fma_f32 v[60:61], v[30:31], v[98:99], v[60:61]
	v_pk_fma_f32 v[62:63], v[30:31], v[100:101], v[62:63]
	v_pk_fma_f32 v[64:65], v[30:31], v[102:103], v[64:65]
	ds_read_b128 v[88:91], v120 offset:1792
	ds_read_b128 v[92:95], v120 offset:1808
	ds_read_b128 v[96:99], v120 offset:1824
	ds_read_b128 v[100:103], v120 offset:1840
	s_waitcnt lgkmcnt(8)
	v_pk_fma_f32 v[34:35], v[12:13], v[104:105], v[34:35]
	v_pk_fma_f32 v[36:37], v[12:13], v[106:107], v[36:37]
	v_pk_fma_f32 v[38:39], v[12:13], v[108:109], v[38:39]
	v_pk_fma_f32 v[40:41], v[12:13], v[110:111], v[40:41]
	v_pk_fma_f32 v[42:43], v[12:13], v[112:113], v[42:43]
	v_pk_fma_f32 v[44:45], v[12:13], v[114:115], v[44:45]
	v_pk_fma_f32 v[46:47], v[12:13], v[116:117], v[46:47]
	v_pk_fma_f32 v[48:49], v[12:13], v[118:119], v[48:49]
	ds_read_b128 v[104:107], v120 offset:1856
	ds_read_b128 v[108:111], v120 offset:1872
	ds_read_b128 v[112:115], v120 offset:1888
	ds_read_b128 v[116:119], v120 offset:1904
	s_waitcnt lgkmcnt(8)
	v_pk_fma_f32 v[50:51], v[12:13], v[72:73], v[50:51]
	v_pk_fma_f32 v[52:53], v[12:13], v[74:75], v[52:53]
	v_pk_fma_f32 v[54:55], v[12:13], v[76:77], v[54:55]
	v_pk_fma_f32 v[56:57], v[12:13], v[78:79], v[56:57]
	v_pk_fma_f32 v[58:59], v[12:13], v[80:81], v[58:59]
	v_pk_fma_f32 v[60:61], v[12:13], v[82:83], v[60:61]
	v_pk_fma_f32 v[62:63], v[12:13], v[84:85], v[62:63]
	v_pk_fma_f32 v[64:65], v[12:13], v[86:87], v[64:65]
	ds_read_b128 v[72:75], v120 offset:1920
	ds_read_b128 v[76:79], v120 offset:1936
	ds_read_b128 v[80:83], v120 offset:1952
	ds_read_b128 v[84:87], v120 offset:1968
	s_waitcnt lgkmcnt(8)
	v_pk_fma_f32 v[34:35], v[32:33], v[88:89], v[34:35]
	v_pk_fma_f32 v[36:37], v[32:33], v[90:91], v[36:37]
	v_pk_fma_f32 v[38:39], v[32:33], v[92:93], v[38:39]
	v_pk_fma_f32 v[40:41], v[32:33], v[94:95], v[40:41]
	v_pk_fma_f32 v[42:43], v[32:33], v[96:97], v[42:43]
	v_pk_fma_f32 v[44:45], v[32:33], v[98:99], v[44:45]
	v_pk_fma_f32 v[46:47], v[32:33], v[100:101], v[46:47]
	v_pk_fma_f32 v[48:49], v[32:33], v[102:103], v[48:49]
	ds_read_b128 v[88:91], v120 offset:1984
	ds_read_b128 v[92:95], v120 offset:2000
	ds_read_b128 v[96:99], v120 offset:2016
	ds_read_b128 v[100:103], v120 offset:2032
	s_waitcnt lgkmcnt(8)
	v_pk_fma_f32 v[50:51], v[32:33], v[104:105], v[50:51]
	v_pk_fma_f32 v[52:53], v[32:33], v[106:107], v[52:53]
	v_pk_fma_f32 v[54:55], v[32:33], v[108:109], v[54:55]
	v_pk_fma_f32 v[56:57], v[32:33], v[110:111], v[56:57]
	v_pk_fma_f32 v[58:59], v[32:33], v[112:113], v[58:59]
	v_pk_fma_f32 v[60:61], v[32:33], v[114:115], v[60:61]
	v_pk_fma_f32 v[62:63], v[32:33], v[116:117], v[62:63]
	v_pk_fma_f32 v[64:65], v[32:33], v[118:119], v[64:65]
	s_waitcnt lgkmcnt(4)
	v_pk_fma_f32 v[34:35], v[14:15], v[72:73], v[34:35]
	v_pk_fma_f32 v[36:37], v[14:15], v[74:75], v[36:37]
	v_pk_fma_f32 v[38:39], v[14:15], v[76:77], v[38:39]
	v_pk_fma_f32 v[40:41], v[14:15], v[78:79], v[40:41]
	v_pk_fma_f32 v[42:43], v[14:15], v[80:81], v[42:43]
	v_pk_fma_f32 v[44:45], v[14:15], v[82:83], v[44:45]
	v_pk_fma_f32 v[46:47], v[14:15], v[84:85], v[46:47]
	v_pk_fma_f32 v[48:49], v[14:15], v[86:87], v[48:49]
	s_waitcnt lgkmcnt(0)
	v_pk_fma_f32 v[50:51], v[14:15], v[88:89], v[50:51]
	v_pk_fma_f32 v[52:53], v[14:15], v[90:91], v[52:53]
	v_pk_fma_f32 v[54:55], v[14:15], v[92:93], v[54:55]
	v_pk_fma_f32 v[56:57], v[14:15], v[94:95], v[56:57]
	v_pk_fma_f32 v[58:59], v[14:15], v[96:97], v[58:59]
	v_pk_fma_f32 v[60:61], v[14:15], v[98:99], v[60:61]
	v_pk_fma_f32 v[62:63], v[14:15], v[100:101], v[62:63]
	v_pk_fma_f32 v[64:65], v[14:15], v[102:103], v[64:65]
	v_bfe_u32 v72, v34, 16, 1
	v_bfe_u32 v73, v35, 16, 1
	v_bfe_u32 v74, v36, 16, 1
	v_bfe_u32 v75, v37, 16, 1
	v_bfe_u32 v76, v38, 16, 1
	v_bfe_u32 v77, v39, 16, 1
	v_bfe_u32 v78, v40, 16, 1
	v_bfe_u32 v79, v41, 16, 1
	v_bfe_u32 v80, v42, 16, 1
	v_bfe_u32 v81, v43, 16, 1
	v_bfe_u32 v82, v44, 16, 1
	v_bfe_u32 v83, v45, 16, 1
	v_bfe_u32 v84, v46, 16, 1
	v_bfe_u32 v85, v47, 16, 1
	v_bfe_u32 v86, v48, 16, 1
	v_bfe_u32 v87, v49, 16, 1
	v_bfe_u32 v88, v50, 16, 1
	v_bfe_u32 v89, v51, 16, 1
	v_bfe_u32 v90, v52, 16, 1
	v_bfe_u32 v91, v53, 16, 1
	v_bfe_u32 v92, v54, 16, 1
	v_bfe_u32 v93, v55, 16, 1
	v_bfe_u32 v94, v56, 16, 1
	v_bfe_u32 v95, v57, 16, 1
	v_bfe_u32 v96, v58, 16, 1
	v_bfe_u32 v97, v59, 16, 1
	v_bfe_u32 v98, v60, 16, 1
	v_bfe_u32 v99, v61, 16, 1
	v_bfe_u32 v100, v62, 16, 1
	v_bfe_u32 v101, v63, 16, 1
	v_bfe_u32 v102, v64, 16, 1
	v_bfe_u32 v103, v65, 16, 1
	v_add3_u32 v34, v34, v72, s77
	v_add3_u32 v35, v35, v73, s77
	v_add3_u32 v36, v36, v74, s77
	v_add3_u32 v37, v37, v75, s77
	v_add3_u32 v38, v38, v76, s77
	v_add3_u32 v39, v39, v77, s77
	v_add3_u32 v40, v40, v78, s77
	v_add3_u32 v41, v41, v79, s77
	v_add3_u32 v42, v42, v80, s77
	v_add3_u32 v43, v43, v81, s77
	v_add3_u32 v44, v44, v82, s77
	v_add3_u32 v45, v45, v83, s77
	v_add3_u32 v46, v46, v84, s77
	v_add3_u32 v47, v47, v85, s77
	v_add3_u32 v48, v48, v86, s77
	v_add3_u32 v49, v49, v87, s77
	v_add3_u32 v50, v50, v88, s77
	v_add3_u32 v51, v51, v89, s77
	v_add3_u32 v52, v52, v90, s77
	v_add3_u32 v53, v53, v91, s77
	v_add3_u32 v54, v54, v92, s77
	v_add3_u32 v55, v55, v93, s77
	v_add3_u32 v56, v56, v94, s77
	v_add3_u32 v57, v57, v95, s77
	v_add3_u32 v58, v58, v96, s77
	v_add3_u32 v59, v59, v97, s77
	v_add3_u32 v60, v60, v98, s77
	v_add3_u32 v61, v61, v99, s77
	v_add3_u32 v62, v62, v100, s77
	v_add3_u32 v63, v63, v101, s77
	v_add3_u32 v64, v64, v102, s77
	v_add3_u32 v65, v65, v103, s77
	global_store_short_d16_hi v[124:125], v34, off
	s_nop 0
	v_lshl_add_u64 v[124:125], v[124:125], 0, s[36:37]
	global_store_short_d16_hi v[124:125], v35, off
	s_nop 0
	v_lshl_add_u64 v[124:125], v[124:125], 0, s[36:37]
	global_store_short_d16_hi v[124:125], v36, off
	s_nop 0
	v_lshl_add_u64 v[124:125], v[124:125], 0, s[36:37]
	global_store_short_d16_hi v[124:125], v37, off
	s_nop 0
	v_lshl_add_u64 v[124:125], v[124:125], 0, s[36:37]
	global_store_short_d16_hi v[124:125], v38, off
	s_nop 0
	v_lshl_add_u64 v[124:125], v[124:125], 0, s[36:37]
	global_store_short_d16_hi v[124:125], v39, off
	s_nop 0
	v_lshl_add_u64 v[124:125], v[124:125], 0, s[36:37]
	global_store_short_d16_hi v[124:125], v40, off
	s_nop 0
	v_lshl_add_u64 v[124:125], v[124:125], 0, s[36:37]
	global_store_short_d16_hi v[124:125], v41, off
	s_nop 0
	v_lshl_add_u64 v[124:125], v[124:125], 0, s[36:37]
	global_store_short_d16_hi v[124:125], v42, off
	s_nop 0
	v_lshl_add_u64 v[124:125], v[124:125], 0, s[36:37]
	global_store_short_d16_hi v[124:125], v43, off
	s_nop 0
	v_lshl_add_u64 v[124:125], v[124:125], 0, s[36:37]
	global_store_short_d16_hi v[124:125], v44, off
	s_nop 0
	v_lshl_add_u64 v[124:125], v[124:125], 0, s[36:37]
	global_store_short_d16_hi v[124:125], v45, off
	s_nop 0
	v_lshl_add_u64 v[124:125], v[124:125], 0, s[36:37]
	global_store_short_d16_hi v[124:125], v46, off
	s_nop 0
	v_lshl_add_u64 v[124:125], v[124:125], 0, s[36:37]
	global_store_short_d16_hi v[124:125], v47, off
	s_nop 0
	v_lshl_add_u64 v[124:125], v[124:125], 0, s[36:37]
	global_store_short_d16_hi v[124:125], v48, off
	s_nop 0
	v_lshl_add_u64 v[124:125], v[124:125], 0, s[36:37]
	global_store_short_d16_hi v[124:125], v49, off
	s_nop 0
	v_lshl_add_u64 v[124:125], v[124:125], 0, s[36:37]
	global_store_short_d16_hi v[124:125], v50, off
	s_nop 0
	v_lshl_add_u64 v[124:125], v[124:125], 0, s[36:37]
	global_store_short_d16_hi v[124:125], v51, off
	s_nop 0
	v_lshl_add_u64 v[124:125], v[124:125], 0, s[36:37]
	global_store_short_d16_hi v[124:125], v52, off
	s_nop 0
	v_lshl_add_u64 v[124:125], v[124:125], 0, s[36:37]
	global_store_short_d16_hi v[124:125], v53, off
	s_nop 0
	v_lshl_add_u64 v[124:125], v[124:125], 0, s[36:37]
	global_store_short_d16_hi v[124:125], v54, off
	s_nop 0
	v_lshl_add_u64 v[124:125], v[124:125], 0, s[36:37]
	global_store_short_d16_hi v[124:125], v55, off
	s_nop 0
	v_lshl_add_u64 v[124:125], v[124:125], 0, s[36:37]
	global_store_short_d16_hi v[124:125], v56, off
	s_nop 0
	v_lshl_add_u64 v[124:125], v[124:125], 0, s[36:37]
	global_store_short_d16_hi v[124:125], v57, off
	s_nop 0
	v_lshl_add_u64 v[124:125], v[124:125], 0, s[36:37]
	global_store_short_d16_hi v[124:125], v58, off
	s_nop 0
	v_lshl_add_u64 v[124:125], v[124:125], 0, s[36:37]
	global_store_short_d16_hi v[124:125], v59, off
	s_nop 0
	v_lshl_add_u64 v[124:125], v[124:125], 0, s[36:37]
	global_store_short_d16_hi v[124:125], v60, off
	s_nop 0
	v_lshl_add_u64 v[124:125], v[124:125], 0, s[36:37]
	global_store_short_d16_hi v[124:125], v61, off
	s_nop 0
	v_lshl_add_u64 v[124:125], v[124:125], 0, s[36:37]
	global_store_short_d16_hi v[124:125], v62, off
	s_nop 0
	v_lshl_add_u64 v[124:125], v[124:125], 0, s[36:37]
	global_store_short_d16_hi v[124:125], v63, off
	s_nop 0
	v_lshl_add_u64 v[124:125], v[124:125], 0, s[36:37]
	global_store_short_d16_hi v[124:125], v64, off
	s_nop 0
	v_lshl_add_u64 v[124:125], v[124:125], 0, s[36:37]
	global_store_short_d16_hi v[124:125], v65, off
	s_nop 0
	v_lshl_add_u64 v[124:125], v[124:125], 0, s[36:37]
	s_branch .LBB0_159
